# plus second LDS tile buffer in four K=1024 GEMM mainloops (one workgroup barrier per half-step instead of two); barrier state words moved to LDS offset 73728
# baseline (speedup 1.0000x reference)
; #define LAS __attribute__((address_space(3)))
; DI unsigned xb_add(unsigned* p, unsigned v) { return __hip_atomic_fetch_add(p, v, __ATOMIC_RELAXED, __HIP_MEMORY_SCOPE_AGENT); }
; DI unsigned xb_xcc_id() { return (unsigned)__builtin_amdgcn_s_getreg((3 << 11) | 20) & 0xFu; }
; DI XcdBarrier xcd_barrier_post(unsigned* bar, volatile LAS unsigned* st) {
;   XcdBarrier b; b.bar = bar; b.x = xb_xcc_id(); b.st = st;
;   if (threadIdx.x == 0) (void)xb_add(&bar[XB_XCNT(b.x)], 1u);
;   return b;
; __global__ void __launch_bounds__(256, 2) fwd_megakernel(Params p) {
;     ...
;   __shared__ __attribute__((aligned(16))) unsigned xb_words[4];
;   if (threadIdx.x < 4) xb_words[threadIdx.x] = 0u;
;   __syncthreads();
;   XcdBarrier gbar = xcd_barrier_post((unsigned*)(ws + OFF_BAR), (volatile LAS unsigned*)&xb_words);
_Z14fwd_megakernel6Params:
	v_and_b32_e32 v160, 0x3ff, v0
	v_writelane_b32 v255, s2, 0
	v_cmp_gt_u32_e32 vcc, 4, v160
	s_nop 0
	v_writelane_b32 v255, s3, 1
	s_mov_b64 s[2:3], s[0:1]
	s_load_dword s0, s[0:1], 0x210
	s_nop 0
	s_load_dwordx2 s[26:27], s[2:3], 0x208
	s_load_dwordx2 s[22:23], s[2:3], 0x80
	s_add_u32 s8, s2, 0x208
	s_addc_u32 s9, s3, 0
	s_waitcnt lgkmcnt(0)
	v_writelane_b32 v255, s0, 2
	s_and_saveexec_b64 s[4:5], vcc
	v_mov_b32_e32 v1, 0x12000
	v_lshl_add_u32 v1, v160, 2, v1
	v_mov_b32_e32 v2, 0
	ds_write_b32 v1, v2
	s_or_b64 exec, exec, s[4:5]
	s_add_u32 s0, s22, 0x1c100000
	s_addc_u32 s1, s23, 0
	v_writelane_b32 v255, s0, 3
	s_waitcnt lgkmcnt(0)
	s_barrier
	v_writelane_b32 v255, s1, 4
	s_getreg_b32 s0, hwreg(HW_REG_XCC_ID, 0, 4)
	s_and_b32 s24, s0, 15
	v_readlane_b32 s0, v255, 0
	v_readlane_b32 s1, v255, 1
	s_mov_b32 s1, 0
	v_writelane_b32 v255, s0, 0
	v_mov_b64_e32 v[18:19], s[22:23]
	s_nop 0
	v_writelane_b32 v255, s1, 1
	v_cmp_eq_u32_e64 s[0:1], 0, v160
	s_mov_b64 s[6:7], exec
	s_nop 0
	v_writelane_b32 v255, s0, 5
	s_nop 1
	v_writelane_b32 v255, s1, 6
	s_and_b64 s[0:1], s[6:7], s[0:1]
	s_mov_b64 exec, s[0:1]
	s_cbranch_execz .LBB0_6
	s_mov_b64 s[12:13], exec
	v_mbcnt_lo_u32_b32 v1, s12, 0
	v_mbcnt_hi_u32_b32 v1, s13, v1
	v_cmp_eq_u32_e32 vcc, 0, v1
	v_mov_b64_e32 v[18:19], s[22:23]
	s_and_saveexec_b64 s[10:11], vcc
	s_cbranch_execz .LBB0_5
	s_lshl_b32 s0, s24, 8
	s_bcnt1_i32_b64 s1, s[12:13]
	v_mov_b32_e32 v1, s0
	v_mov_b32_e32 v2, s1
	v_readlane_b32 s0, v255, 3
	v_readlane_b32 s1, v255, 4
	v_mov_b64_e32 v[18:19], s[22:23]
	s_nop 3
	global_atomic_add v1, v2, s[0:1] offset:1024

; DI unsigned xb_ld(unsigned* p)              { return __hip_atomic_load(p, __ATOMIC_RELAXED, __HIP_MEMORY_SCOPE_AGENT); }
; DI void xcd_barrier_complete(unsigned* bar, unsigned x, unsigned& nloc, unsigned& nx) {
;   const unsigned G = gridDim.x * gridDim.y * gridDim.z;
;   unsigned sum, cnt, mine, sp = 0u;
;   for (;;) {
;     sum = 0u; cnt = 0u; mine = 0u;
; #pragma unroll
;     for (unsigned j = 0; j < 16; ++j) { const unsigned c = xb_ld(&bar[XB_XCNT(j)]); sum += c; cnt += (c > 0u) ? 1u : 0u; mine = (j == x) ? c : mine; }
; DI void xcd_barrier(const XcdBarrier& b) {
;   asm volatile("s_waitcnt vmcnt(0)" ::: "memory");
;   __syncthreads();
;   if (threadIdx.x == 0) {
;     unsigned* bar = b.bar;
;     __builtin_amdgcn_s_waitcnt(0);
;     unsigned nloc = b.st[0], nx = b.st[1];
;     if (nloc == 0u) { xcd_barrier_complete(bar, b.x, nloc, nx); b.st[0] = nloc; b.st[1] = nx; }
.LBB0_47:
	s_or_b64 exec, exec, s[6:7]
	s_waitcnt vmcnt(0)
	s_barrier
	s_mov_b64 s[6:7], exec
	v_readlane_b32 s0, v255, 5
	v_readlane_b32 s1, v255, 6
	s_and_b64 s[0:1], s[6:7], s[0:1]
	s_mov_b64 exec, s[0:1]
	s_cbranch_execz .LBB0_99
	v_mov_b32_e32 v0, 0x12000
	s_waitcnt vmcnt(0) expcnt(0) lgkmcnt(0)
	ds_read_b32 v2, v0
	v_mov_b32_e32 v0, 0x12004
	ds_read_b32 v0, v0
	s_waitcnt lgkmcnt(1)
	v_cmp_ne_u32_e32 vcc, 0, v2
	s_cbranch_vccnz .LBB0_63
	s_add_u32 s8, s22, 0x1c100200
	s_addc_u32 s9, s23, 0
	s_add_u32 s10, s22, 0x1c100400
	s_addc_u32 s11, s23, 0
	s_add_u32 s12, s22, 0x1c100500
	s_addc_u32 s13, s23, 0
	s_add_u32 s14, s22, 0x1c100600
	s_addc_u32 s15, s23, 0
	s_add_u32 s16, s22, 0x1c100700
	s_addc_u32 s17, s23, 0
	s_add_u32 s18, s22, 0x1c100800
	s_addc_u32 s19, s23, 0
	s_add_u32 s20, s22, 0x1c100900
	s_addc_u32 s21, s23, 0
	s_add_u32 s28, s22, 0x1c100a00
	s_addc_u32 s29, s23, 0
	s_add_u32 s30, s22, 0x1c100b00
	s_addc_u32 s31, s23, 0
	s_add_u32 s34, s22, 0x1c100c00
	s_addc_u32 s35, s23, 0
	s_add_u32 s36, s22, 0x1c100d00
	s_addc_u32 s37, s23, 0
	s_add_u32 s38, s22, 0x1c100e00
	s_addc_u32 s39, s23, 0
	s_add_u32 s40, s22, 0x1c100f00
	s_addc_u32 s41, s23, 0
	s_add_u32 s42, s22, 0x1c101000
	s_load_dword s0, s[2:3], 0x210
	s_addc_u32 s43, s23, 0
	s_add_u32 s44, s22, 0x1c101100
	s_addc_u32 s45, s23, 0
	s_add_u32 s46, s22, 0x1c101200
	s_addc_u32 s47, s23, 0
	s_waitcnt lgkmcnt(0)
	s_mul_i32 s0, s27, s0
	s_add_u32 s48, s22, 0x1c101300
	s_mul_i32 s0, s0, s26
	s_addc_u32 s49, s23, 0
	s_mov_b32 s1, 1
	v_mov_b32_e32 v16, 0
	s_branch .LBB0_51

; DI unsigned xb_ld(unsigned* p)              { return __hip_atomic_load(p, __ATOMIC_RELAXED, __HIP_MEMORY_SCOPE_AGENT); }
; DI void xcd_barrier_complete(unsigned* bar, unsigned x, unsigned& nloc, unsigned& nx) {
;     ...
;     for (unsigned j = 0; j < 16; ++j) { const unsigned c = xb_ld(&bar[XB_XCNT(j)]); sum += c; cnt += (c > 0u) ? 1u : 0u; mine = (j == x) ? c : mine; }
;     if (sum == G) break;
;     __builtin_amdgcn_s_sleep(1);
;     if ((++sp & 255u) == 0u) { if (xb_ld(&bar[XB_TMO])) break; if (sp > XB_SPIN_CAP) { atomicAdd(&bar[XB_TMO], 1u); break; } }
;   }
;   nloc = mine > 0u ? mine : 1u; nx = cnt > 0u ? cnt : 1u;
; }
; DI void xcd_barrier(const XcdBarrier& b) {
;   asm volatile("s_waitcnt vmcnt(0)" ::: "memory");
;   __syncthreads();
;   if (threadIdx.x == 0) {
;     unsigned* bar = b.bar;
;     __builtin_amdgcn_s_waitcnt(0);
;     unsigned nloc = b.st[0], nx = b.st[1];
;     if (nloc == 0u) { xcd_barrier_complete(bar, b.x, nloc, nx); b.st[0] = nloc; b.st[1] = nx; }
.LBB0_62:
	s_cmp_eq_u32 s24, 0
	s_cselect_b64 vcc, -1, 0
	s_cmp_eq_u32 s24, 1
	v_cndmask_b32_e32 v16, 0, v15, vcc
	s_cselect_b64 vcc, -1, 0
	s_cmp_eq_u32 s24, 2
	v_cndmask_b32_e32 v16, v16, v0, vcc
	s_cselect_b64 vcc, -1, 0
	s_cmp_eq_u32 s24, 3
	v_cndmask_b32_e32 v16, v16, v1, vcc
	s_cselect_b64 vcc, -1, 0
	s_cmp_eq_u32 s24, 4
	v_cndmask_b32_e32 v16, v16, v2, vcc
	s_cselect_b64 vcc, -1, 0
	s_cmp_eq_u32 s24, 5
	v_cndmask_b32_e32 v16, v16, v3, vcc
	s_cselect_b64 vcc, -1, 0
	s_cmp_eq_u32 s24, 6
	v_cndmask_b32_e32 v16, v16, v4, vcc
	s_cselect_b64 vcc, -1, 0
	s_cmp_eq_u32 s24, 7
	v_cndmask_b32_e32 v16, v16, v5, vcc
	s_cselect_b64 vcc, -1, 0
	s_cmp_eq_u32 s24, 8
	v_cndmask_b32_e32 v16, v16, v6, vcc
	s_cselect_b64 vcc, -1, 0
	s_cmp_eq_u32 s24, 9
	v_cndmask_b32_e32 v16, v16, v7, vcc
	s_cselect_b64 vcc, -1, 0
	s_cmp_eq_u32 s24, 10
	v_cndmask_b32_e32 v16, v16, v8, vcc
	s_cselect_b64 vcc, -1, 0
	s_cmp_eq_u32 s24, 11
	v_cndmask_b32_e32 v16, v16, v9, vcc
	s_cselect_b64 vcc, -1, 0
	s_cmp_eq_u32 s24, 12
	v_cndmask_b32_e32 v16, v16, v10, vcc
	s_cselect_b64 vcc, -1, 0
	s_cmp_eq_u32 s24, 13
	v_cndmask_b32_e32 v16, v16, v11, vcc
	s_cselect_b64 vcc, -1, 0
	s_cmp_eq_u32 s24, 14
	v_cndmask_b32_e32 v16, v16, v12, vcc
	s_cselect_b64 vcc, -1, 0
	s_cmp_eq_u32 s24, 15
	v_cndmask_b32_e32 v16, v16, v13, vcc
	s_cselect_b64 vcc, -1, 0
	v_cndmask_b32_e32 v16, v16, v14, vcc
	v_cmp_ne_u32_e32 vcc, 0, v15
	s_nop 1
	v_cndmask_b32_e64 v15, 0, 1, vcc
	v_cmp_ne_u32_e32 vcc, 0, v0
	s_nop 1
	v_addc_co_u32_e32 v0, vcc, 0, v15, vcc
	v_cmp_ne_u32_e32 vcc, 0, v1
	s_nop 1
	v_cndmask_b32_e64 v1, 0, 1, vcc
	v_cmp_ne_u32_e32 vcc, 0, v2
	v_max_u32_e32 v2, 1, v16
	s_nop 0
	v_addc_co_u32_e32 v0, vcc, v0, v1, vcc
	v_cmp_ne_u32_e32 vcc, 0, v3
	s_nop 1
	v_cndmask_b32_e64 v1, 0, 1, vcc
	v_cmp_ne_u32_e32 vcc, 0, v4
	s_nop 1
	v_addc_co_u32_e32 v0, vcc, v0, v1, vcc
	v_cmp_ne_u32_e32 vcc, 0, v5
	s_nop 1
	v_cndmask_b32_e64 v1, 0, 1, vcc
	v_cmp_ne_u32_e32 vcc, 0, v6
	s_nop 1
	v_addc_co_u32_e32 v0, vcc, v0, v1, vcc
	v_cmp_ne_u32_e32 vcc, 0, v7
	s_nop 1
	v_cndmask_b32_e64 v1, 0, 1, vcc
	v_cmp_ne_u32_e32 vcc, 0, v8
	s_nop 1
	v_addc_co_u32_e32 v0, vcc, v0, v1, vcc
	v_cmp_ne_u32_e32 vcc, 0, v9
	s_nop 1
	v_cndmask_b32_e64 v1, 0, 1, vcc
	v_cmp_ne_u32_e32 vcc, 0, v10
	s_nop 1
	v_addc_co_u32_e32 v0, vcc, v0, v1, vcc
	v_cmp_ne_u32_e32 vcc, 0, v11
	s_nop 1
	v_cndmask_b32_e64 v1, 0, 1, vcc
	v_cmp_ne_u32_e32 vcc, 0, v12
	s_nop 1
	v_addc_co_u32_e32 v0, vcc, v0, v1, vcc
	v_cmp_ne_u32_e32 vcc, 0, v13
	s_nop 1
	v_cndmask_b32_e64 v1, 0, 1, vcc
	v_cmp_ne_u32_e32 vcc, 0, v14
	s_nop 1
	v_addc_co_u32_e32 v0, vcc, v0, v1, vcc
	v_mov_b32_e32 v1, 0x12000
	v_max_u32_e32 v0, 1, v0
	ds_write_b32 v1, v2
	v_mov_b32_e32 v1, 0x12004
	ds_write_b32 v1, v0

; #define MFMA(a, b, c) __builtin_amdgcn_mfma_f32_32x32x16_bf16((a), (b), (c), 0, 0, 0)
; DI void gt_compute(const bf16* asr, const bf16* bsr, f32x16& acc0, f32x16& acc1, f32x16& acc2, f32x16& acc3) {
;   bf16x8 a[4], b0[4], b1[4], b2[4], b3[4];
; #pragma unroll
;   for (int kk = 0; kk < 4; ++kk) {
;     a[kk] = *(const bf16x8*)(asr + kk * 16);
;     b0[kk] = *(const bf16x8*)(bsr + kk * 16);
;     b1[kk] = *(const bf16x8*)(bsr + 32 * LDT + kk * 16);
;     b2[kk] = *(const bf16x8*)(bsr + 64 * LDT + kk * 16);
;     b3[kk] = *(const bf16x8*)(bsr + 96 * LDT + kk * 16);
;   }
;   __builtin_amdgcn_sched_barrier(0);
;   __builtin_amdgcn_s_setprio(2);
; #pragma unroll
;   for (int kk = 0; kk < 4; ++kk) {
;     acc0 = MFMA(a[kk], b0[kk], acc0); acc1 = MFMA(a[kk], b1[kk], acc1); acc2 = MFMA(a[kk], b2[kk], acc2); acc3 = MFMA(a[kk], b3[kk], acc3);
;   }
;   __builtin_amdgcn_s_setprio(0);
;   __builtin_amdgcn_sched_barrier(0);
; DI void gemm_mainloop(const bf16* __restrict__ A, int lda, const bf16* __restrict__ Bt, int ldb, int K, int m0, int n0,
;                       bf16* As, bf16* Bs, f32x16& acc0, f32x16& acc1, f32x16& acc2, f32x16& acc3) {
;     ...
;   for (int k0 = 0; k0 < K; k0 += 128) {
;     __syncthreads();
;     gt_store(t0, asw, bsw);
;     __syncthreads();
;     if (k0 + 128 < K) gt_load(t0, ap, bp, lda, ldb, KW(k0 + 128));
;     gt_compute(asr, bsr, acc0, acc1, acc2, acc3);
;     __syncthreads();
;     gt_store(t1, asw, bsw);
;     __syncthreads();
;     if (k0 + 192 < K) gt_load(t1, ap, bp, lda, ldb, KW(k0 + 192));
;     gt_compute(asr, bsr, acc0, acc1, acc2, acc3);
.LBB0_228:
	v_add_u32_e32 v142, 0x9000, v142
	v_add_u32_e32 v130, 0x9000, v130
	ds_read_b128 v[146:149], v142
	ds_read_b128 v[150:153], v142 offset:32
	ds_read_b128 v[154:157], v130 offset:18432
	ds_read_b128 v[162:165], v130 offset:18464
	ds_read_b128 v[166:169], v130 offset:23040
	ds_read_b128 v[170:173], v130 offset:23072
	ds_read_b128 v[174:177], v130 offset:27648
	ds_read_b128 v[178:181], v130 offset:27680
	ds_read_b128 v[182:185], v130 offset:32256
	ds_read_b128 v[186:189], v130 offset:32288
	ds_read_b128 v[190:193], v142 offset:64
	ds_read_b128 v[194:197], v142 offset:96
	ds_read_b128 v[198:201], v130 offset:18496
	ds_read_b128 v[202:205], v130 offset:18528
	ds_read_b128 v[206:209], v130 offset:23104
	ds_read_b128 v[210:213], v130 offset:23136
	ds_read_b128 v[214:217], v130 offset:27712
	ds_read_b128 v[218:221], v130 offset:27744
	ds_read_b128 v[222:225], v130 offset:32320
	ds_read_b128 v[226:229], v130 offset:32352
	v_add_u32_e32 v142, 0xffff7000, v142
	v_add_u32_e32 v130, 0xffff7000, v130
	s_setprio 2
	s_waitcnt lgkmcnt(14)
	v_mfma_f32_32x32x16_bf16 v[48:63], v[146:149], v[154:157], v[48:63]
	v_mfma_f32_32x32x16_bf16 v[32:47], v[146:149], v[166:169], v[32:47]
	s_waitcnt lgkmcnt(13)
	v_mfma_f32_32x32x16_bf16 v[16:31], v[146:149], v[174:177], v[16:31]
	s_waitcnt lgkmcnt(11)
	v_mfma_f32_32x32x16_bf16 v[0:15], v[146:149], v[182:185], v[0:15]
	v_mfma_f32_32x32x16_bf16 v[48:63], v[150:153], v[162:165], v[48:63]
	v_mfma_f32_32x32x16_bf16 v[32:47], v[150:153], v[170:173], v[32:47]
	v_mfma_f32_32x32x16_bf16 v[16:31], v[150:153], v[178:181], v[16:31]
	s_waitcnt lgkmcnt(10)
	v_mfma_f32_32x32x16_bf16 v[0:15], v[150:153], v[186:189], v[0:15]
	s_waitcnt lgkmcnt(7)
	v_mfma_f32_32x32x16_bf16 v[48:63], v[190:193], v[198:201], v[48:63]
	s_waitcnt lgkmcnt(5)
	v_mfma_f32_32x32x16_bf16 v[32:47], v[190:193], v[206:209], v[32:47]
	s_waitcnt lgkmcnt(3)
	v_mfma_f32_32x32x16_bf16 v[16:31], v[190:193], v[214:217], v[16:31]
	s_waitcnt lgkmcnt(1)
	v_mfma_f32_32x32x16_bf16 v[0:15], v[190:193], v[222:225], v[0:15]
	v_mfma_f32_32x32x16_bf16 v[48:63], v[194:197], v[202:205], v[48:63]
	v_mfma_f32_32x32x16_bf16 v[32:47], v[194:197], v[210:213], v[32:47]
	v_mfma_f32_32x32x16_bf16 v[16:31], v[194:197], v[218:221], v[16:31]
	s_waitcnt lgkmcnt(0)
	v_mfma_f32_32x32x16_bf16 v[0:15], v[194:197], v[226:229], v[0:15]
	s_setprio 0
	s_add_i32 s0, s28, 0xffffff80
	s_cmpk_lt_u32 s0, 0x380
	s_mov_b64 s[20:21], s[28:29]
	s_cbranch_scc0 .LBB0_233
.LBB0_229:
	s_add_u32 s28, s20, 0x80
	s_addc_u32 s29, s21, 0
	s_cmpk_gt_u32 s20, 0x37f
	s_waitcnt vmcnt(13)
	ds_write_b128 v140, v[72:75]
	ds_write_b128 v140, v[64:67] offset:4608
	ds_write_b128 v140, v[68:71] offset:9216
	s_waitcnt vmcnt(11)
	ds_write_b128 v140, v[80:83] offset:13824
	ds_write_b128 v140, v[76:79] offset:18432
	s_waitcnt vmcnt(10)
	ds_write_b128 v140, v[84:87] offset:23040
	s_waitcnt vmcnt(9)
	ds_write_b128 v140, v[96:99] offset:27648
	s_waitcnt vmcnt(8)
	ds_write_b128 v140, v[100:103] offset:32256
	s_waitcnt lgkmcnt(0)
	s_barrier
	s_cbranch_scc1 .LBB0_231
	s_cmp_lt_i32 s28, s15
	s_cselect_b32 s1, 0, -1
	s_cselect_b32 s0, 0, 0xfffffc00
	s_add_u32 s30, s18, s20
	s_addc_u32 s31, s19, s21
	s_add_u32 s0, s30, s0
	s_addc_u32 s1, s31, s1
	s_lshl_b64 s[0:1], s[0:1], 1
	v_lshl_add_u64 v[72:73], v[136:137], 0, s[0:1]
	v_add_co_u32_e32 v64, vcc, s48, v72
	v_lshl_add_u64 v[96:97], v[138:139], 0, s[0:1]
	s_nop 0
	v_addc_co_u32_e32 v65, vcc, 0, v73, vcc
	v_add_co_u32_e32 v68, vcc, 0x20000, v72
	s_nop 1
	v_addc_co_u32_e32 v69, vcc, 0, v73, vcc
	v_add_co_u32_e32 v80, vcc, 0x30000, v72
	global_load_dwordx4 v[64:67], v[64:65], off offset:256
	s_nop 0
	global_load_dwordx4 v[68:71], v[68:69], off offset:256
	v_addc_co_u32_e32 v81, vcc, 0, v73, vcc
	v_add_co_u32_e32 v84, vcc, 0x10000, v96
	global_load_dwordx4 v[72:75], v[72:73], off offset:256
	s_nop 0
	global_load_dwordx4 v[76:79], v[96:97], off offset:256
	v_addc_co_u32_e32 v85, vcc, 0, v97, vcc
	v_add_co_u32_e32 v98, vcc, 0x20000, v96
	global_load_dwordx4 v[80:83], v[80:81], off offset:256
	s_nop 0
	global_load_dwordx4 v[84:87], v[84:85], off offset:256
	v_addc_co_u32_e32 v99, vcc, 0, v97, vcc
	v_add_co_u32_e32 v100, vcc, 0x30000, v96
	s_nop 1
	v_addc_co_u32_e32 v101, vcc, 0, v97, vcc
	global_load_dwordx4 v[96:99], v[98:99], off offset:256
	s_nop 0
	global_load_dwordx4 v[100:103], v[100:101], off offset:256
; #define MFMA(a, b, c) __builtin_amdgcn_mfma_f32_32x32x16_bf16((a), (b), (c), 0, 0, 0)
; DI void gt_compute(const bf16* asr, const bf16* bsr, f32x16& acc0, f32x16& acc1, f32x16& acc2, f32x16& acc3) {
;   bf16x8 a[4], b0[4], b1[4], b2[4], b3[4];
; #pragma unroll
;   for (int kk = 0; kk < 4; ++kk) {
;     a[kk] = *(const bf16x8*)(asr + kk * 16);
;     b0[kk] = *(const bf16x8*)(bsr + kk * 16);
;     b1[kk] = *(const bf16x8*)(bsr + 32 * LDT + kk * 16);
;     b2[kk] = *(const bf16x8*)(bsr + 64 * LDT + kk * 16);
;     b3[kk] = *(const bf16x8*)(bsr + 96 * LDT + kk * 16);
;   }
;   __builtin_amdgcn_sched_barrier(0);
;   __builtin_amdgcn_s_setprio(2);
; #pragma unroll
;   for (int kk = 0; kk < 4; ++kk) {
;     acc0 = MFMA(a[kk], b0[kk], acc0); acc1 = MFMA(a[kk], b1[kk], acc1); acc2 = MFMA(a[kk], b2[kk], acc2); acc3 = MFMA(a[kk], b3[kk], acc3);
;   }
;   __builtin_amdgcn_s_setprio(0);
;   __builtin_amdgcn_sched_barrier(0);
; DI void gemm_mainloop(const bf16* __restrict__ A, int lda, const bf16* __restrict__ Bt, int ldb, int K, int m0, int n0,
;                       bf16* As, bf16* Bs, f32x16& acc0, f32x16& acc1, f32x16& acc2, f32x16& acc3) {
;     ...
;   for (int k0 = 0; k0 < K; k0 += 128) {
;     __syncthreads();
;     gt_store(t0, asw, bsw);
;     __syncthreads();
;     if (k0 + 128 < K) gt_load(t0, ap, bp, lda, ldb, KW(k0 + 128));
;     gt_compute(asr, bsr, acc0, acc1, acc2, acc3);
;     __syncthreads();
;     gt_store(t1, asw, bsw);
;     __syncthreads();
;     if (k0 + 192 < K) gt_load(t1, ap, bp, lda, ldb, KW(k0 + 192));
;     gt_compute(asr, bsr, acc0, acc1, acc2, acc3);
.LBB0_231:
	ds_read_b128 v[146:149], v142
	ds_read_b128 v[150:153], v142 offset:32
	ds_read_b128 v[154:157], v130 offset:18432
	ds_read_b128 v[162:165], v130 offset:18464
	ds_read_b128 v[166:169], v130 offset:23040
	ds_read_b128 v[170:173], v130 offset:23072
	ds_read_b128 v[174:177], v130 offset:27648
	ds_read_b128 v[178:181], v130 offset:27680
	ds_read_b128 v[182:185], v130 offset:32256
	ds_read_b128 v[186:189], v130 offset:32288
	ds_read_b128 v[190:193], v142 offset:64
	ds_read_b128 v[194:197], v142 offset:96
	ds_read_b128 v[198:201], v130 offset:18496
	ds_read_b128 v[202:205], v130 offset:18528
	ds_read_b128 v[206:209], v130 offset:23104
	ds_read_b128 v[210:213], v130 offset:23136
	ds_read_b128 v[214:217], v130 offset:27712
	ds_read_b128 v[218:221], v130 offset:27744
	ds_read_b128 v[222:225], v130 offset:32320
	ds_read_b128 v[226:229], v130 offset:32352
	s_setprio 2
	s_waitcnt lgkmcnt(14)
	v_mfma_f32_32x32x16_bf16 v[48:63], v[146:149], v[154:157], v[48:63]
	v_mfma_f32_32x32x16_bf16 v[32:47], v[146:149], v[166:169], v[32:47]
	s_waitcnt lgkmcnt(13)
	v_mfma_f32_32x32x16_bf16 v[16:31], v[146:149], v[174:177], v[16:31]
	s_waitcnt lgkmcnt(11)
	v_mfma_f32_32x32x16_bf16 v[0:15], v[146:149], v[182:185], v[0:15]
	v_mfma_f32_32x32x16_bf16 v[48:63], v[150:153], v[162:165], v[48:63]
	v_mfma_f32_32x32x16_bf16 v[32:47], v[150:153], v[170:173], v[32:47]
	v_mfma_f32_32x32x16_bf16 v[16:31], v[150:153], v[178:181], v[16:31]
	s_waitcnt lgkmcnt(10)
	v_mfma_f32_32x32x16_bf16 v[0:15], v[150:153], v[186:189], v[0:15]
	s_waitcnt lgkmcnt(7)
	v_mfma_f32_32x32x16_bf16 v[48:63], v[190:193], v[198:201], v[48:63]
	s_waitcnt lgkmcnt(5)
	v_mfma_f32_32x32x16_bf16 v[32:47], v[190:193], v[206:209], v[32:47]
	s_waitcnt lgkmcnt(3)
	v_mfma_f32_32x32x16_bf16 v[16:31], v[190:193], v[214:217], v[16:31]
	s_waitcnt lgkmcnt(1)
	v_mfma_f32_32x32x16_bf16 v[0:15], v[190:193], v[222:225], v[0:15]
	v_mfma_f32_32x32x16_bf16 v[48:63], v[194:197], v[202:205], v[48:63]
	v_mfma_f32_32x32x16_bf16 v[32:47], v[194:197], v[210:213], v[32:47]
	v_mfma_f32_32x32x16_bf16 v[16:31], v[194:197], v[218:221], v[16:31]
	s_waitcnt lgkmcnt(0)
	v_mfma_f32_32x32x16_bf16 v[0:15], v[194:197], v[226:229], v[0:15]
	s_setprio 0
	s_cmpk_gt_u32 s20, 0x33f
	v_add_u32_e32 v140, 0x9000, v140
	s_waitcnt vmcnt(5)
	ds_write_b128 v140, v[104:107]
	ds_write_b128 v140, v[88:91] offset:4608
	ds_write_b128 v140, v[92:95] offset:9216
	s_waitcnt vmcnt(3)
	ds_write_b128 v140, v[112:115] offset:13824
	ds_write_b128 v140, v[108:111] offset:18432
	s_waitcnt vmcnt(2)
	ds_write_b128 v140, v[116:119] offset:23040
	s_waitcnt vmcnt(1)
	ds_write_b128 v140, v[120:123] offset:27648
	s_waitcnt vmcnt(0)
	ds_write_b128 v140, v[124:127] offset:32256
	v_add_u32_e32 v140, 0xffff7000, v140
	s_waitcnt lgkmcnt(0)
	s_barrier
	s_cbranch_scc1 .LBB0_228
	s_cmp_lt_i32 s20, s17
	s_cselect_b32 s1, 0, -1
	s_cselect_b32 s0, 0, 0xfffffc00
	s_add_u32 s20, s18, s20
	s_addc_u32 s21, s19, s21
	s_add_u32 s0, s20, s0
	s_addc_u32 s1, s21, s1
	s_lshl_b64 s[0:1], s[0:1], 1
	v_lshl_add_u64 v[104:105], v[136:137], 0, s[0:1]
	v_add_co_u32_e32 v106, vcc, s48, v104
	v_lshl_add_u64 v[120:121], v[138:139], 0, s[0:1]
	s_nop 0
	v_addc_co_u32_e32 v107, vcc, 0, v105, vcc
	v_add_co_u32_e32 v108, vcc, 0x20000, v104
	s_nop 1
	v_addc_co_u32_e32 v109, vcc, 0, v105, vcc
	v_add_co_u32_e32 v112, vcc, 0x30000, v104
	global_load_dwordx4 v[88:91], v[106:107], off offset:384
	global_load_dwordx4 v[92:95], v[108:109], off offset:384
	v_addc_co_u32_e32 v113, vcc, 0, v105, vcc
	v_add_co_u32_e32 v116, vcc, 0x10000, v120
	global_load_dwordx4 v[104:107], v[104:105], off offset:384
	s_nop 0
	global_load_dwordx4 v[108:111], v[120:121], off offset:384
	v_addc_co_u32_e32 v117, vcc, 0, v121, vcc
	v_add_co_u32_e32 v122, vcc, 0x20000, v120
	global_load_dwordx4 v[112:115], v[112:113], off offset:384
	s_nop 0
	global_load_dwordx4 v[116:119], v[116:117], off offset:384
	v_addc_co_u32_e32 v123, vcc, 0, v121, vcc
	v_add_co_u32_e32 v124, vcc, 0x30000, v120
	s_nop 1
	v_addc_co_u32_e32 v125, vcc, 0, v121, vcc
	global_load_dwordx4 v[120:123], v[122:123], off offset:384
	s_nop 0
	global_load_dwordx4 v[124:127], v[124:125], off offset:384
	s_branch .LBB0_228

; DI unsigned xb_ld(unsigned* p)              { return __hip_atomic_load(p, __ATOMIC_RELAXED, __HIP_MEMORY_SCOPE_AGENT); }
; DI void xcd_barrier_complete(unsigned* bar, unsigned x, unsigned& nloc, unsigned& nx) {
;   const unsigned G = gridDim.x * gridDim.y * gridDim.z;
;   unsigned sum, cnt, mine, sp = 0u;
;   for (;;) {
;     sum = 0u; cnt = 0u; mine = 0u;
; #pragma unroll
;     for (unsigned j = 0; j < 16; ++j) { const unsigned c = xb_ld(&bar[XB_XCNT(j)]); sum += c; cnt += (c > 0u) ? 1u : 0u; mine = (j == x) ? c : mine; }
; DI void xcd_barrier(const XcdBarrier& b) {
;   asm volatile("s_waitcnt vmcnt(0)" ::: "memory");
;   __syncthreads();
;   if (threadIdx.x == 0) {
;     unsigned* bar = b.bar;
;     __builtin_amdgcn_s_waitcnt(0);
;     unsigned nloc = b.st[0], nx = b.st[1];
;     if (nloc == 0u) { xcd_barrier_complete(bar, b.x, nloc, nx); b.st[0] = nloc; b.st[1] = nx; }
.LBB0_268:
	s_waitcnt vmcnt(0)
	s_waitcnt lgkmcnt(0)
	s_barrier
	s_mov_b64 s[6:7], exec
	v_readlane_b32 s0, v255, 5
	v_readlane_b32 s1, v255, 6
	s_and_b64 s[0:1], s[6:7], s[0:1]
	s_mov_b64 exec, s[0:1]
	s_cbranch_execz .LBB0_320
	v_mov_b32_e32 v0, 0x12000
	s_waitcnt vmcnt(0) expcnt(0) lgkmcnt(0)
	ds_read_b32 v2, v0
	v_mov_b32_e32 v0, 0x12004
	ds_read_b32 v0, v0
	s_waitcnt lgkmcnt(1)
	v_cmp_ne_u32_e32 vcc, 0, v2
	s_cbranch_vccnz .LBB0_284
	s_add_u32 s8, s22, 0x1c100200
	s_addc_u32 s9, s23, 0
	s_add_u32 s10, s22, 0x1c100400
	s_addc_u32 s11, s23, 0
	s_add_u32 s12, s22, 0x1c100500
	s_addc_u32 s13, s23, 0
	s_add_u32 s14, s22, 0x1c100600
	s_addc_u32 s15, s23, 0
	s_add_u32 s16, s22, 0x1c100700
	s_addc_u32 s17, s23, 0
	s_add_u32 s18, s22, 0x1c100800
	s_addc_u32 s19, s23, 0
	s_add_u32 s20, s22, 0x1c100900
	s_addc_u32 s21, s23, 0
	s_add_u32 s28, s22, 0x1c100a00
	s_addc_u32 s29, s23, 0
	s_add_u32 s30, s22, 0x1c100b00
	s_addc_u32 s31, s23, 0
	s_add_u32 s34, s22, 0x1c100c00
	s_addc_u32 s35, s23, 0
	s_add_u32 s38, s22, 0x1c100d00
	s_addc_u32 s39, s23, 0
	s_add_u32 s40, s22, 0x1c100e00
	s_addc_u32 s41, s23, 0
	s_add_u32 s42, s22, 0x1c100f00
	s_addc_u32 s43, s23, 0
	s_add_u32 s44, s22, 0x1c101000
	s_load_dword s0, s[2:3], 0x210
	s_addc_u32 s45, s23, 0
	s_add_u32 s46, s22, 0x1c101100
	s_addc_u32 s47, s23, 0
	s_add_u32 s48, s22, 0x1c101200
	s_addc_u32 s49, s23, 0
	s_waitcnt lgkmcnt(0)
	s_mul_i32 s0, s27, s0
	s_add_u32 s50, s22, 0x1c101300
	s_mul_i32 s0, s0, s26
	s_addc_u32 s51, s23, 0
	s_mov_b32 s1, 1
	v_mov_b32_e32 v16, 0
	s_branch .LBB0_272

; DI unsigned xb_ld(unsigned* p)              { return __hip_atomic_load(p, __ATOMIC_RELAXED, __HIP_MEMORY_SCOPE_AGENT); }
; DI void xcd_barrier_complete(unsigned* bar, unsigned x, unsigned& nloc, unsigned& nx) {
;   const unsigned G = gridDim.x * gridDim.y * gridDim.z;
;   unsigned sum, cnt, mine, sp = 0u;
;   for (;;) {
;     sum = 0u; cnt = 0u; mine = 0u;
; #pragma unroll
;     for (unsigned j = 0; j < 16; ++j) { const unsigned c = xb_ld(&bar[XB_XCNT(j)]); sum += c; cnt += (c > 0u) ? 1u : 0u; mine = (j == x) ? c : mine; }
; DI void xcd_barrier(const XcdBarrier& b) {
;   asm volatile("s_waitcnt vmcnt(0)" ::: "memory");
;   __syncthreads();
;   if (threadIdx.x == 0) {
;     unsigned* bar = b.bar;
;     __builtin_amdgcn_s_waitcnt(0);
;     unsigned nloc = b.st[0], nx = b.st[1];
;     if (nloc == 0u) { xcd_barrier_complete(bar, b.x, nloc, nx); b.st[0] = nloc; b.st[1] = nx; }
.LBB0_350:
	s_waitcnt vmcnt(0)
	s_waitcnt vmcnt(63) expcnt(7) lgkmcnt(15)
	s_barrier
	s_mov_b64 s[6:7], exec
	v_readlane_b32 s0, v255, 5
	v_readlane_b32 s1, v255, 6
	s_and_b64 s[0:1], s[6:7], s[0:1]
	s_mov_b64 exec, s[0:1]
	s_cbranch_execz .LBB0_402
	v_mov_b32_e32 v0, 0x12000
	s_waitcnt vmcnt(0) expcnt(0) lgkmcnt(0)
	ds_read_b32 v2, v0
	v_mov_b32_e32 v0, 0x12004
	ds_read_b32 v0, v0
	s_waitcnt lgkmcnt(1)
	v_cmp_ne_u32_e32 vcc, 0, v2
	s_cbranch_vccnz .LBB0_366
	s_add_u32 s8, s22, 0x1c100200
	s_addc_u32 s9, s23, 0
	s_add_u32 s10, s22, 0x1c100400
	s_addc_u32 s11, s23, 0
	s_add_u32 s12, s22, 0x1c100500
	s_addc_u32 s13, s23, 0
	s_add_u32 s14, s22, 0x1c100600
	s_addc_u32 s15, s23, 0
	s_add_u32 s16, s22, 0x1c100700
	s_addc_u32 s17, s23, 0
	s_add_u32 s18, s22, 0x1c100800
	s_addc_u32 s19, s23, 0
	s_add_u32 s28, s22, 0x1c100900
	s_addc_u32 s29, s23, 0
	s_add_u32 s30, s22, 0x1c100a00
	s_addc_u32 s31, s23, 0
	s_add_u32 s34, s22, 0x1c100b00
	s_addc_u32 s35, s23, 0
	s_add_u32 s38, s22, 0x1c100c00
	s_addc_u32 s39, s23, 0
	s_add_u32 s40, s22, 0x1c100d00
	s_addc_u32 s41, s23, 0
	s_add_u32 s42, s22, 0x1c100e00
	s_addc_u32 s43, s23, 0
	s_add_u32 s44, s22, 0x1c100f00
	s_addc_u32 s45, s23, 0
	s_add_u32 s46, s22, 0x1c101000
	s_load_dword s0, s[2:3], 0x210
	s_addc_u32 s47, s23, 0
	s_add_u32 s48, s22, 0x1c101100
	s_addc_u32 s49, s23, 0
	s_add_u32 s50, s22, 0x1c101200
	s_addc_u32 s51, s23, 0
	s_waitcnt lgkmcnt(0)
	s_mul_i32 s0, s27, s0
	s_add_u32 s52, s22, 0x1c101300
	s_mul_i32 s0, s0, s26
	s_addc_u32 s53, s23, 0
	s_mov_b32 s1, 1
	v_mov_b32_e32 v16, 0
	s_branch .LBB0_354

; DI unsigned xb_ld(unsigned* p)              { return __hip_atomic_load(p, __ATOMIC_RELAXED, __HIP_MEMORY_SCOPE_AGENT); }
; DI void xcd_barrier_complete(unsigned* bar, unsigned x, unsigned& nloc, unsigned& nx) {
;   const unsigned G = gridDim.x * gridDim.y * gridDim.z;
;   unsigned sum, cnt, mine, sp = 0u;
;   for (;;) {
;     sum = 0u; cnt = 0u; mine = 0u;
; #pragma unroll
;     for (unsigned j = 0; j < 16; ++j) { const unsigned c = xb_ld(&bar[XB_XCNT(j)]); sum += c; cnt += (c > 0u) ? 1u : 0u; mine = (j == x) ? c : mine; }
; DI void xcd_barrier(const XcdBarrier& b) {
;   asm volatile("s_waitcnt vmcnt(0)" ::: "memory");
;   __syncthreads();
;   if (threadIdx.x == 0) {
;     unsigned* bar = b.bar;
;     __builtin_amdgcn_s_waitcnt(0);
;     unsigned nloc = b.st[0], nx = b.st[1];
;     if (nloc == 0u) { xcd_barrier_complete(bar, b.x, nloc, nx); b.st[0] = nloc; b.st[1] = nx; }
.LBB0_424:
	s_waitcnt vmcnt(0)
	v_readlane_b32 s0, v255, 5
	v_readlane_b32 s1, v255, 6
	s_barrier
	s_and_saveexec_b64 s[12:13], s[0:1]
	s_cbranch_execz .LBB0_476
	v_mov_b32_e32 v0, 0x12000
	s_waitcnt vmcnt(0) expcnt(0) lgkmcnt(0)
	ds_read_b32 v2, v0
	v_mov_b32_e32 v0, 0x12004
	ds_read_b32 v0, v0
	s_waitcnt lgkmcnt(1)
	v_cmp_ne_u32_e32 vcc, 0, v2
	s_cbranch_vccnz .LBB0_440
	s_add_u32 s14, s22, 0x1c100200
	s_addc_u32 s15, s23, 0
	s_add_u32 s28, s22, 0x1c100400
	s_addc_u32 s29, s23, 0
	s_add_u32 s30, s22, 0x1c100500
	s_addc_u32 s31, s23, 0
	s_add_u32 s34, s22, 0x1c100600
	s_addc_u32 s35, s23, 0
	s_add_u32 s40, s22, 0x1c100700
	s_addc_u32 s41, s23, 0
	s_add_u32 s42, s22, 0x1c100800
	s_addc_u32 s43, s23, 0
	s_add_u32 s44, s22, 0x1c100900
	s_addc_u32 s45, s23, 0
	s_add_u32 s46, s22, 0x1c100a00
	s_addc_u32 s47, s23, 0
	s_add_u32 s48, s22, 0x1c100b00
	s_addc_u32 s49, s23, 0
	s_add_u32 s50, s22, 0x1c100c00
	s_addc_u32 s51, s23, 0
	s_add_u32 s52, s22, 0x1c100d00
	s_addc_u32 s53, s23, 0
	s_add_u32 s54, s22, 0x1c100e00
	s_addc_u32 s55, s23, 0
	s_add_u32 s58, s22, 0x1c100f00
	s_addc_u32 s59, s23, 0
	s_add_u32 s60, s22, 0x1c101000
	s_addc_u32 s61, s23, 0
	s_add_u32 s62, s22, 0x1c101100
	s_addc_u32 s63, s23, 0
	s_add_u32 s64, s22, 0x1c101200
	v_readlane_b32 s0, v255, 2
	s_addc_u32 s65, s23, 0
	s_mul_i32 s4, s27, s0
	s_add_u32 s66, s22, 0x1c101300
	s_mul_i32 s4, s4, s26
	s_addc_u32 s67, s23, 0
	s_mov_b32 s5, 1
	v_mov_b32_e32 v16, 0
	s_branch .LBB0_428

; #define MFMA(a, b, c) __builtin_amdgcn_mfma_f32_32x32x16_bf16((a), (b), (c), 0, 0, 0)
; DI void gt_compute(const bf16* asr, const bf16* bsr, f32x16& acc0, f32x16& acc1, f32x16& acc2, f32x16& acc3) {
;   bf16x8 a[4], b0[4], b1[4], b2[4], b3[4];
; #pragma unroll
;   for (int kk = 0; kk < 4; ++kk) {
;     a[kk] = *(const bf16x8*)(asr + kk * 16);
;     b0[kk] = *(const bf16x8*)(bsr + kk * 16);
;     b1[kk] = *(const bf16x8*)(bsr + 32 * LDT + kk * 16);
;     b2[kk] = *(const bf16x8*)(bsr + 64 * LDT + kk * 16);
;     b3[kk] = *(const bf16x8*)(bsr + 96 * LDT + kk * 16);
;   }
;   __builtin_amdgcn_sched_barrier(0);
;   __builtin_amdgcn_s_setprio(2);
; #pragma unroll
;   for (int kk = 0; kk < 4; ++kk) {
;     acc0 = MFMA(a[kk], b0[kk], acc0); acc1 = MFMA(a[kk], b1[kk], acc1); acc2 = MFMA(a[kk], b2[kk], acc2); acc3 = MFMA(a[kk], b3[kk], acc3);
;   }
;   __builtin_amdgcn_s_setprio(0);
;   __builtin_amdgcn_sched_barrier(0);
; DI void gemm_mainloop(const bf16* __restrict__ A, int lda, const bf16* __restrict__ Bt, int ldb, int K, int m0, int n0,
;                       bf16* As, bf16* Bs, f32x16& acc0, f32x16& acc1, f32x16& acc2, f32x16& acc3) {
;     ...
;   for (int k0 = 0; k0 < K; k0 += 128) {
;     __syncthreads();
;     gt_store(t0, asw, bsw);
;     __syncthreads();
;     if (k0 + 128 < K) gt_load(t0, ap, bp, lda, ldb, KW(k0 + 128));
;     gt_compute(asr, bsr, acc0, acc1, acc2, acc3);
;     __syncthreads();
;     gt_store(t1, asw, bsw);
;     __syncthreads();
;     if (k0 + 192 < K) gt_load(t1, ap, bp, lda, ldb, KW(k0 + 192));
;     gt_compute(asr, bsr, acc0, acc1, acc2, acc3);
.LBB0_480:
	v_add_u32_e32 v138, 0x9000, v138
	v_add_u32_e32 v128, 0x9000, v128
	ds_read_b128 v[142:145], v138
	ds_read_b128 v[146:149], v138 offset:32
	ds_read_b128 v[150:153], v128 offset:18432
	ds_read_b128 v[154:157], v128 offset:18464
	ds_read_b128 v[166:169], v128 offset:23040
	ds_read_b128 v[170:173], v128 offset:23072
	ds_read_b128 v[174:177], v128 offset:27648
	ds_read_b128 v[178:181], v128 offset:27680
	ds_read_b128 v[182:185], v128 offset:32256
	ds_read_b128 v[186:189], v128 offset:32288
	ds_read_b128 v[190:193], v138 offset:64
	ds_read_b128 v[194:197], v138 offset:96
	ds_read_b128 v[198:201], v128 offset:18496
	ds_read_b128 v[202:205], v128 offset:18528
	ds_read_b128 v[206:209], v128 offset:23104
	ds_read_b128 v[210:213], v128 offset:23136
	ds_read_b128 v[214:217], v128 offset:27712
	ds_read_b128 v[228:231], v128 offset:27744
	ds_read_b128 v[232:235], v128 offset:32320
	ds_read_b128 v[236:239], v128 offset:32352
	v_add_u32_e32 v138, 0xffff7000, v138
	v_add_u32_e32 v128, 0xffff7000, v128
	s_setprio 2
	s_waitcnt lgkmcnt(14)
	v_mfma_f32_32x32x16_bf16 v[48:63], v[142:145], v[150:153], v[48:63]
	v_mfma_f32_32x32x16_bf16 v[32:47], v[142:145], v[166:169], v[32:47]
	s_waitcnt lgkmcnt(13)
	v_mfma_f32_32x32x16_bf16 v[16:31], v[142:145], v[174:177], v[16:31]
	s_waitcnt lgkmcnt(11)
	v_mfma_f32_32x32x16_bf16 v[0:15], v[142:145], v[182:185], v[0:15]
	v_mfma_f32_32x32x16_bf16 v[48:63], v[146:149], v[154:157], v[48:63]
	v_mfma_f32_32x32x16_bf16 v[32:47], v[146:149], v[170:173], v[32:47]
	v_mfma_f32_32x32x16_bf16 v[16:31], v[146:149], v[178:181], v[16:31]
	s_waitcnt lgkmcnt(10)
	v_mfma_f32_32x32x16_bf16 v[0:15], v[146:149], v[186:189], v[0:15]
	s_waitcnt lgkmcnt(7)
	v_mfma_f32_32x32x16_bf16 v[48:63], v[190:193], v[198:201], v[48:63]
	s_waitcnt lgkmcnt(5)
	v_mfma_f32_32x32x16_bf16 v[32:47], v[190:193], v[206:209], v[32:47]
	s_waitcnt lgkmcnt(3)
	v_mfma_f32_32x32x16_bf16 v[16:31], v[190:193], v[214:217], v[16:31]
	s_waitcnt lgkmcnt(1)
	v_mfma_f32_32x32x16_bf16 v[0:15], v[190:193], v[232:235], v[0:15]
	v_mfma_f32_32x32x16_bf16 v[48:63], v[194:197], v[202:205], v[48:63]
	v_mfma_f32_32x32x16_bf16 v[32:47], v[194:197], v[210:213], v[32:47]
	v_mfma_f32_32x32x16_bf16 v[16:31], v[194:197], v[228:231], v[16:31]
	s_waitcnt lgkmcnt(0)
	v_mfma_f32_32x32x16_bf16 v[0:15], v[194:197], v[236:239], v[0:15]
	s_setprio 0
	s_add_i32 s6, s34, 0xffffff80
	s_cmpk_lt_u32 s6, 0x380
	s_mov_b64 s[30:31], s[34:35]
	s_cbranch_scc0 .LBB0_478
.LBB0_481:
	s_add_u32 s34, s30, 0x80
	s_addc_u32 s35, s31, 0
	s_cmpk_gt_u32 s30, 0x37f
	s_waitcnt vmcnt(63) expcnt(7) lgkmcnt(15)
	s_waitcnt vmcnt(13)
	ds_write_b128 v136, v[72:75]
	ds_write_b128 v136, v[64:67] offset:4608
	ds_write_b128 v136, v[68:71] offset:9216
	s_waitcnt vmcnt(11)
	ds_write_b128 v136, v[80:83] offset:13824
	ds_write_b128 v136, v[76:79] offset:18432
	s_waitcnt vmcnt(10)
	ds_write_b128 v136, v[84:87] offset:23040
	s_waitcnt vmcnt(9)
	ds_write_b128 v136, v[96:99] offset:27648
	s_waitcnt vmcnt(8)
	ds_write_b128 v136, v[104:107] offset:32256
	s_waitcnt lgkmcnt(0)
	s_barrier
	s_cbranch_scc1 .LBB0_483
	s_cmp_lt_i32 s34, s44
	s_cselect_b32 s7, 0, -1
	s_cselect_b32 s6, 0, 0xfffffc00
	s_add_u32 s46, s28, s30
	s_addc_u32 s47, s29, s31
	s_add_u32 s6, s46, s6
	s_addc_u32 s7, s47, s7
	s_lshl_b64 s[6:7], s[6:7], 1
	v_lshl_add_u64 v[72:73], v[132:133], 0, s[6:7]
	v_add_co_u32_e32 v64, vcc, s4, v72
	v_lshl_add_u64 v[96:97], v[134:135], 0, s[6:7]
	s_nop 0
	v_addc_co_u32_e32 v65, vcc, 0, v73, vcc
	v_add_co_u32_e32 v68, vcc, 0x20000, v72
	s_nop 1
	v_addc_co_u32_e32 v69, vcc, 0, v73, vcc
	v_add_co_u32_e32 v80, vcc, 0x30000, v72
	global_load_dwordx4 v[64:67], v[64:65], off offset:256
	s_nop 0
	global_load_dwordx4 v[68:71], v[68:69], off offset:256
	v_addc_co_u32_e32 v81, vcc, 0, v73, vcc
	v_add_co_u32_e32 v84, vcc, 0x10000, v96
	global_load_dwordx4 v[72:75], v[72:73], off offset:256
	s_nop 0
	global_load_dwordx4 v[76:79], v[96:97], off offset:256
	v_addc_co_u32_e32 v85, vcc, 0, v97, vcc
	v_add_co_u32_e32 v98, vcc, 0x20000, v96
	global_load_dwordx4 v[80:83], v[80:81], off offset:256
	s_nop 0
	global_load_dwordx4 v[84:87], v[84:85], off offset:256
	v_addc_co_u32_e32 v99, vcc, 0, v97, vcc
	v_add_co_u32_e32 v104, vcc, 0x30000, v96
	s_nop 1
	v_addc_co_u32_e32 v105, vcc, 0, v97, vcc
	global_load_dwordx4 v[96:99], v[98:99], off offset:256
	s_nop 0
	global_load_dwordx4 v[104:107], v[104:105], off offset:256
; #define MFMA(a, b, c) __builtin_amdgcn_mfma_f32_32x32x16_bf16((a), (b), (c), 0, 0, 0)
; DI void xcd_barrier(const XcdBarrier& b) {
;   asm volatile("s_waitcnt vmcnt(0)" ::: "memory");
;   __syncthreads();
;   if (threadIdx.x == 0) {
;     unsigned* bar = b.bar;
;     __builtin_amdgcn_s_waitcnt(0);
;     unsigned nloc = b.st[0], nx = b.st[1];
;     if (nloc == 0u) { xcd_barrier_complete(bar, b.x, nloc, nx); b.st[0] = nloc; b.st[1] = nx; }
; DI void gt_compute(const bf16* asr, const bf16* bsr, f32x16& acc0, f32x16& acc1, f32x16& acc2, f32x16& acc3) {
;   bf16x8 a[4], b0[4], b1[4], b2[4], b3[4];
; #pragma unroll
;   for (int kk = 0; kk < 4; ++kk) {
;     a[kk] = *(const bf16x8*)(asr + kk * 16);
;     b0[kk] = *(const bf16x8*)(bsr + kk * 16);
;     b1[kk] = *(const bf16x8*)(bsr + 32 * LDT + kk * 16);
;     b2[kk] = *(const bf16x8*)(bsr + 64 * LDT + kk * 16);
;     b3[kk] = *(const bf16x8*)(bsr + 96 * LDT + kk * 16);
;   }
;   __builtin_amdgcn_sched_barrier(0);
;   __builtin_amdgcn_s_setprio(2);
; #pragma unroll
;   for (int kk = 0; kk < 4; ++kk) {
;     acc0 = MFMA(a[kk], b0[kk], acc0); acc1 = MFMA(a[kk], b1[kk], acc1); acc2 = MFMA(a[kk], b2[kk], acc2); acc3 = MFMA(a[kk], b3[kk], acc3);
;   }
;   __builtin_amdgcn_s_setprio(0);
;   __builtin_amdgcn_sched_barrier(0);
; DI void gemm_mainloop(const bf16* __restrict__ A, int lda, const bf16* __restrict__ Bt, int ldb, int K, int m0, int n0,
;                       bf16* As, bf16* Bs, f32x16& acc0, f32x16& acc1, f32x16& acc2, f32x16& acc3) {
;     ...
;   for (int k0 = 0; k0 < K; k0 += 128) {
;     __syncthreads();
;     gt_store(t0, asw, bsw);
;     __syncthreads();
;     if (k0 + 128 < K) gt_load(t0, ap, bp, lda, ldb, KW(k0 + 128));
;     gt_compute(asr, bsr, acc0, acc1, acc2, acc3);
;     __syncthreads();
;     gt_store(t1, asw, bsw);
;     __syncthreads();
;     if (k0 + 192 < K) gt_load(t1, ap, bp, lda, ldb, KW(k0 + 192));
;     gt_compute(asr, bsr, acc0, acc1, acc2, acc3);
.LBB0_483:
	ds_read_b128 v[142:145], v138
	ds_read_b128 v[146:149], v138 offset:32
	ds_read_b128 v[150:153], v128 offset:18432
	ds_read_b128 v[154:157], v128 offset:18464
	ds_read_b128 v[166:169], v128 offset:23040
	ds_read_b128 v[170:173], v128 offset:23072
	ds_read_b128 v[174:177], v128 offset:27648
	ds_read_b128 v[178:181], v128 offset:27680
	ds_read_b128 v[182:185], v128 offset:32256
	ds_read_b128 v[186:189], v128 offset:32288
	ds_read_b128 v[190:193], v138 offset:64
	ds_read_b128 v[194:197], v138 offset:96
	ds_read_b128 v[198:201], v128 offset:18496
	ds_read_b128 v[202:205], v128 offset:18528
	ds_read_b128 v[206:209], v128 offset:23104
	ds_read_b128 v[210:213], v128 offset:23136
	ds_read_b128 v[214:217], v128 offset:27712
	ds_read_b128 v[228:231], v128 offset:27744
	ds_read_b128 v[232:235], v128 offset:32320
	ds_read_b128 v[236:239], v128 offset:32352
	s_setprio 2
	s_waitcnt lgkmcnt(14)
	v_mfma_f32_32x32x16_bf16 v[48:63], v[142:145], v[150:153], v[48:63]
	v_mfma_f32_32x32x16_bf16 v[32:47], v[142:145], v[166:169], v[32:47]
	s_waitcnt lgkmcnt(13)
	v_mfma_f32_32x32x16_bf16 v[16:31], v[142:145], v[174:177], v[16:31]
	s_waitcnt lgkmcnt(11)
	v_mfma_f32_32x32x16_bf16 v[0:15], v[142:145], v[182:185], v[0:15]
	v_mfma_f32_32x32x16_bf16 v[48:63], v[146:149], v[154:157], v[48:63]
	v_mfma_f32_32x32x16_bf16 v[32:47], v[146:149], v[170:173], v[32:47]
	v_mfma_f32_32x32x16_bf16 v[16:31], v[146:149], v[178:181], v[16:31]
	s_waitcnt lgkmcnt(10)
	v_mfma_f32_32x32x16_bf16 v[0:15], v[146:149], v[186:189], v[0:15]
	s_waitcnt lgkmcnt(7)
	v_mfma_f32_32x32x16_bf16 v[48:63], v[190:193], v[198:201], v[48:63]
	s_waitcnt lgkmcnt(5)
	v_mfma_f32_32x32x16_bf16 v[32:47], v[190:193], v[206:209], v[32:47]
	s_waitcnt lgkmcnt(3)
	v_mfma_f32_32x32x16_bf16 v[16:31], v[190:193], v[214:217], v[16:31]
	s_waitcnt lgkmcnt(1)
	v_mfma_f32_32x32x16_bf16 v[0:15], v[190:193], v[232:235], v[0:15]
	v_mfma_f32_32x32x16_bf16 v[48:63], v[194:197], v[202:205], v[48:63]
	v_mfma_f32_32x32x16_bf16 v[32:47], v[194:197], v[210:213], v[32:47]
	v_mfma_f32_32x32x16_bf16 v[16:31], v[194:197], v[228:231], v[16:31]
	s_waitcnt lgkmcnt(0)
	v_mfma_f32_32x32x16_bf16 v[0:15], v[194:197], v[236:239], v[0:15]
	s_setprio 0
	s_cmpk_gt_u32 s30, 0x33f
	v_add_u32_e32 v136, 0x9000, v136
	s_waitcnt vmcnt(5)
	ds_write_b128 v136, v[100:103]
	ds_write_b128 v136, v[88:91] offset:4608
	ds_write_b128 v136, v[92:95] offset:9216
	s_waitcnt vmcnt(3)
	ds_write_b128 v136, v[112:115] offset:13824
	ds_write_b128 v136, v[108:111] offset:18432
	s_waitcnt vmcnt(2)
	ds_write_b128 v136, v[116:119] offset:23040
	s_waitcnt vmcnt(1)
	ds_write_b128 v136, v[120:123] offset:27648
	s_waitcnt vmcnt(0)
	ds_write_b128 v136, v[124:127] offset:32256
	v_add_u32_e32 v136, 0xffff7000, v136
	s_waitcnt lgkmcnt(0)
	s_barrier
	s_cbranch_scc1 .LBB0_480
	s_cmp_lt_i32 s30, s45
	s_cselect_b32 s7, 0, -1
	s_cselect_b32 s6, 0, 0xfffffc00
	s_add_u32 s30, s28, s30
	s_addc_u32 s31, s29, s31
	s_add_u32 s6, s30, s6
	s_addc_u32 s7, s31, s7
	s_lshl_b64 s[6:7], s[6:7], 1
	v_lshl_add_u64 v[100:101], v[132:133], 0, s[6:7]
	v_add_co_u32_e32 v88, vcc, s4, v100
	v_lshl_add_u64 v[120:121], v[134:135], 0, s[6:7]
	s_nop 0
	v_addc_co_u32_e32 v89, vcc, 0, v101, vcc
	v_add_co_u32_e32 v92, vcc, 0x20000, v100
	s_nop 1
	v_addc_co_u32_e32 v93, vcc, 0, v101, vcc
	v_add_co_u32_e32 v112, vcc, 0x30000, v100
	global_load_dwordx4 v[88:91], v[88:89], off offset:384
	s_nop 0
	global_load_dwordx4 v[92:95], v[92:93], off offset:384
	v_addc_co_u32_e32 v113, vcc, 0, v101, vcc
	v_add_co_u32_e32 v116, vcc, 0x10000, v120
	global_load_dwordx4 v[100:103], v[100:101], off offset:384
	s_nop 0
	global_load_dwordx4 v[108:111], v[120:121], off offset:384
	v_addc_co_u32_e32 v117, vcc, 0, v121, vcc
	v_add_co_u32_e32 v122, vcc, 0x20000, v120
	global_load_dwordx4 v[112:115], v[112:113], off offset:384
	s_nop 0
	global_load_dwordx4 v[116:119], v[116:117], off offset:384
	v_addc_co_u32_e32 v123, vcc, 0, v121, vcc
	v_add_co_u32_e32 v124, vcc, 0x30000, v120
	s_nop 1
	v_addc_co_u32_e32 v125, vcc, 0, v121, vcc
	global_load_dwordx4 v[120:123], v[122:123], off offset:384
	s_nop 0
	global_load_dwordx4 v[124:127], v[124:125], off offset:384
	s_branch .LBB0_480
.LBB0_485:
	s_waitcnt vmcnt(0)
	v_readlane_b32 s0, v255, 5
	v_readlane_b32 s1, v255, 6
	s_waitcnt vmcnt(63) expcnt(7) lgkmcnt(15)
	s_barrier
	s_and_saveexec_b64 s[12:13], s[0:1]
	s_cbranch_execz .LBB0_537
	v_mov_b32_e32 v0, 0x12000
	s_waitcnt vmcnt(0) expcnt(0) lgkmcnt(0)
	ds_read_b32 v2, v0
	v_mov_b32_e32 v0, 0x12004
	ds_read_b32 v0, v0
	s_waitcnt lgkmcnt(1)
	v_cmp_ne_u32_e32 vcc, 0, v2
	s_cbranch_vccnz .LBB0_501
	s_add_u32 s14, s22, 0x1c100200
	s_addc_u32 s15, s23, 0
	s_add_u32 s28, s22, 0x1c100400
	s_addc_u32 s29, s23, 0
	s_add_u32 s30, s22, 0x1c100500
	s_addc_u32 s31, s23, 0
	s_add_u32 s34, s22, 0x1c100600
	s_addc_u32 s35, s23, 0
	s_add_u32 s40, s22, 0x1c100700
	s_addc_u32 s41, s23, 0
	s_add_u32 s42, s22, 0x1c100800
	s_addc_u32 s43, s23, 0
	s_add_u32 s44, s22, 0x1c100900
	s_addc_u32 s45, s23, 0
	s_add_u32 s46, s22, 0x1c100a00
	s_addc_u32 s47, s23, 0
	s_add_u32 s48, s22, 0x1c100b00
	s_addc_u32 s49, s23, 0
	s_add_u32 s50, s22, 0x1c100c00
	s_addc_u32 s51, s23, 0
	s_add_u32 s52, s22, 0x1c100d00
	s_addc_u32 s53, s23, 0
	s_add_u32 s54, s22, 0x1c100e00
	s_addc_u32 s55, s23, 0
	s_add_u32 s58, s22, 0x1c100f00
	s_addc_u32 s59, s23, 0
	s_add_u32 s60, s22, 0x1c101000
	s_addc_u32 s61, s23, 0
	s_add_u32 s62, s22, 0x1c101100
	s_addc_u32 s63, s23, 0
	s_add_u32 s64, s22, 0x1c101200
	v_readlane_b32 s0, v255, 2
	s_addc_u32 s65, s23, 0
	s_mul_i32 s4, s27, s0
	s_add_u32 s66, s22, 0x1c101300
	s_mul_i32 s4, s4, s26
	s_addc_u32 s67, s23, 0
	s_mov_b32 s5, 1
	v_mov_b32_e32 v16, 0
	s_branch .LBB0_489

; DI unsigned xb_ld(unsigned* p)              { return __hip_atomic_load(p, __ATOMIC_RELAXED, __HIP_MEMORY_SCOPE_AGENT); }
; DI void xcd_barrier_complete(unsigned* bar, unsigned x, unsigned& nloc, unsigned& nx) {
;   const unsigned G = gridDim.x * gridDim.y * gridDim.z;
;   unsigned sum, cnt, mine, sp = 0u;
;   for (;;) {
;     sum = 0u; cnt = 0u; mine = 0u;
; #pragma unroll
;     for (unsigned j = 0; j < 16; ++j) { const unsigned c = xb_ld(&bar[XB_XCNT(j)]); sum += c; cnt += (c > 0u) ? 1u : 0u; mine = (j == x) ? c : mine; }
; DI void xcd_barrier(const XcdBarrier& b) {
;   asm volatile("s_waitcnt vmcnt(0)" ::: "memory");
;   __syncthreads();
;   if (threadIdx.x == 0) {
;     unsigned* bar = b.bar;
;     __builtin_amdgcn_s_waitcnt(0);
;     unsigned nloc = b.st[0], nx = b.st[1];
;     if (nloc == 0u) { xcd_barrier_complete(bar, b.x, nloc, nx); b.st[0] = nloc; b.st[1] = nx; }
.LBB0_540:
	s_or_b64 exec, exec, s[28:29]
	s_waitcnt vmcnt(0)
	v_readlane_b32 s0, v255, 5
	v_readlane_b32 s1, v255, 6
	s_barrier
	s_and_saveexec_b64 s[12:13], s[0:1]
	s_cbranch_execz .LBB0_592
	v_mov_b32_e32 v0, 0x12000
	s_waitcnt vmcnt(0) expcnt(0) lgkmcnt(0)
	ds_read_b32 v2, v0
	v_mov_b32_e32 v0, 0x12004
	ds_read_b32 v0, v0
	s_waitcnt lgkmcnt(1)
	v_cmp_ne_u32_e32 vcc, 0, v2
	s_cbranch_vccnz .LBB0_556
	s_add_u32 s14, s22, 0x1c100200
	s_addc_u32 s15, s23, 0
	s_add_u32 s28, s22, 0x1c100400
	s_addc_u32 s29, s23, 0
	s_add_u32 s40, s22, 0x1c100500
	s_addc_u32 s41, s23, 0
	s_add_u32 s42, s22, 0x1c100600
	s_addc_u32 s43, s23, 0
	s_add_u32 s44, s22, 0x1c100700
	s_addc_u32 s45, s23, 0
	s_add_u32 s46, s22, 0x1c100800
	s_addc_u32 s47, s23, 0
	s_add_u32 s48, s22, 0x1c100900
	s_addc_u32 s49, s23, 0
	s_add_u32 s50, s22, 0x1c100a00
	s_addc_u32 s51, s23, 0
	s_add_u32 s52, s22, 0x1c100b00
	s_addc_u32 s53, s23, 0
	s_add_u32 s54, s22, 0x1c100c00
	s_addc_u32 s55, s23, 0
	s_add_u32 s58, s22, 0x1c100d00
	s_addc_u32 s59, s23, 0
	s_add_u32 s60, s22, 0x1c100e00
	s_addc_u32 s61, s23, 0
	s_add_u32 s62, s22, 0x1c100f00
	s_addc_u32 s63, s23, 0
	s_add_u32 s64, s22, 0x1c101000
	s_addc_u32 s65, s23, 0
	s_add_u32 s66, s22, 0x1c101100
	s_addc_u32 s67, s23, 0
	s_add_u32 s68, s22, 0x1c101200
	v_readlane_b32 s0, v255, 2
	s_addc_u32 s69, s23, 0
	s_mul_i32 s4, s27, s0
	s_add_u32 s70, s22, 0x1c101300
	s_mul_i32 s4, s4, s26
	s_addc_u32 s71, s23, 0
	s_mov_b32 s5, 1
	v_mov_b32_e32 v16, 0
	s_branch .LBB0_544

; DI unsigned xb_ld(unsigned* p)              { return __hip_atomic_load(p, __ATOMIC_RELAXED, __HIP_MEMORY_SCOPE_AGENT); }
; DI void xcd_barrier_complete(unsigned* bar, unsigned x, unsigned& nloc, unsigned& nx) {
;   const unsigned G = gridDim.x * gridDim.y * gridDim.z;
;   unsigned sum, cnt, mine, sp = 0u;
;   for (;;) {
;     sum = 0u; cnt = 0u; mine = 0u;
; #pragma unroll
;     for (unsigned j = 0; j < 16; ++j) { const unsigned c = xb_ld(&bar[XB_XCNT(j)]); sum += c; cnt += (c > 0u) ? 1u : 0u; mine = (j == x) ? c : mine; }
; DI void xcd_barrier(const XcdBarrier& b) {
;   asm volatile("s_waitcnt vmcnt(0)" ::: "memory");
;   __syncthreads();
;   if (threadIdx.x == 0) {
;     unsigned* bar = b.bar;
;     __builtin_amdgcn_s_waitcnt(0);
;     unsigned nloc = b.st[0], nx = b.st[1];
;     if (nloc == 0u) { xcd_barrier_complete(bar, b.x, nloc, nx); b.st[0] = nloc; b.st[1] = nx; }
.LBB0_622:
	s_waitcnt vmcnt(0)
	v_readlane_b32 s0, v255, 5
	v_readlane_b32 s1, v255, 6
	s_barrier
	s_and_saveexec_b64 s[8:9], s[0:1]
	s_cbranch_execz .LBB0_674
	v_mov_b32_e32 v0, 0x12000
	s_waitcnt vmcnt(0) expcnt(0) lgkmcnt(0)
	ds_read_b32 v2, v0
	v_mov_b32_e32 v0, 0x12004
	ds_read_b32 v0, v0
	s_waitcnt lgkmcnt(1)
	v_cmp_ne_u32_e32 vcc, 0, v2
	s_cbranch_vccnz .LBB0_638
	s_add_u32 s10, s22, 0x1c100200
	s_addc_u32 s11, s23, 0
	s_add_u32 s12, s22, 0x1c100400
	s_addc_u32 s13, s23, 0
	s_add_u32 s14, s22, 0x1c100500
	s_addc_u32 s15, s23, 0
	s_add_u32 s16, s22, 0x1c100600
	s_addc_u32 s17, s23, 0
	s_add_u32 s18, s22, 0x1c100700
	s_addc_u32 s19, s23, 0
	s_add_u32 s28, s22, 0x1c100800
	s_addc_u32 s29, s23, 0
	s_add_u32 s38, s22, 0x1c100900
	s_addc_u32 s39, s23, 0
	s_add_u32 s40, s22, 0x1c100a00
	s_addc_u32 s41, s23, 0
	s_add_u32 s42, s22, 0x1c100b00
	s_addc_u32 s43, s23, 0
	s_add_u32 s44, s22, 0x1c100c00
	s_addc_u32 s45, s23, 0
	s_add_u32 s46, s22, 0x1c100d00
	s_addc_u32 s47, s23, 0
	s_add_u32 s48, s22, 0x1c100e00
	s_addc_u32 s49, s23, 0
	s_add_u32 s50, s22, 0x1c100f00
	s_addc_u32 s51, s23, 0
	s_add_u32 s52, s22, 0x1c101000
	s_addc_u32 s53, s23, 0
	s_add_u32 s54, s22, 0x1c101100
	s_addc_u32 s55, s23, 0
	s_add_u32 s56, s22, 0x1c101200
	v_readlane_b32 s0, v255, 2
	s_addc_u32 s57, s23, 0
	s_mul_i32 s4, s27, s0
	s_add_u32 s58, s22, 0x1c101300
	s_mul_i32 s4, s4, s26
	s_addc_u32 s59, s23, 0
	s_mov_b32 s5, 1
	v_mov_b32_e32 v16, 0
	s_branch .LBB0_626

; DI unsigned xb_ld(unsigned* p)              { return __hip_atomic_load(p, __ATOMIC_RELAXED, __HIP_MEMORY_SCOPE_AGENT); }
; DI void xcd_barrier_complete(unsigned* bar, unsigned x, unsigned& nloc, unsigned& nx) {
;   const unsigned G = gridDim.x * gridDim.y * gridDim.z;
;   unsigned sum, cnt, mine, sp = 0u;
;   for (;;) {
;     sum = 0u; cnt = 0u; mine = 0u;
; #pragma unroll
;     for (unsigned j = 0; j < 16; ++j) { const unsigned c = xb_ld(&bar[XB_XCNT(j)]); sum += c; cnt += (c > 0u) ? 1u : 0u; mine = (j == x) ? c : mine; }
; DI void xcd_barrier(const XcdBarrier& b) {
;   asm volatile("s_waitcnt vmcnt(0)" ::: "memory");
;   __syncthreads();
;   if (threadIdx.x == 0) {
;     unsigned* bar = b.bar;
;     __builtin_amdgcn_s_waitcnt(0);
;     unsigned nloc = b.st[0], nx = b.st[1];
;     if (nloc == 0u) { xcd_barrier_complete(bar, b.x, nloc, nx); b.st[0] = nloc; b.st[1] = nx; }
.LBB0_755:
	s_or_b64 exec, exec, s[10:11]
	s_waitcnt vmcnt(0)
	v_readlane_b32 s0, v255, 5
	v_readlane_b32 s1, v255, 6
	s_barrier
	s_and_saveexec_b64 s[8:9], s[0:1]
	s_cbranch_execz .LBB0_807
	v_mov_b32_e32 v0, 0x12000
	s_waitcnt vmcnt(0) expcnt(0) lgkmcnt(0)
	ds_read_b32 v2, v0
	v_mov_b32_e32 v0, 0x12004
	ds_read_b32 v0, v0
	s_waitcnt lgkmcnt(1)
	v_cmp_ne_u32_e32 vcc, 0, v2
	s_cbranch_vccnz .LBB0_771
	s_add_u32 s10, s22, 0x1c100200
	s_addc_u32 s11, s23, 0
	s_add_u32 s12, s22, 0x1c100400
	s_addc_u32 s13, s23, 0
	s_add_u32 s14, s22, 0x1c100500
	s_addc_u32 s15, s23, 0
	s_add_u32 s16, s22, 0x1c100600
	s_addc_u32 s17, s23, 0
	s_add_u32 s18, s22, 0x1c100700
	s_addc_u32 s19, s23, 0
	s_add_u32 s28, s22, 0x1c100800
	s_addc_u32 s29, s23, 0
	s_add_u32 s38, s22, 0x1c100900
	s_addc_u32 s39, s23, 0
	s_add_u32 s40, s22, 0x1c100a00
	s_addc_u32 s41, s23, 0
	s_add_u32 s42, s22, 0x1c100b00
	s_addc_u32 s43, s23, 0
	s_add_u32 s44, s22, 0x1c100c00
	s_addc_u32 s45, s23, 0
	s_add_u32 s46, s22, 0x1c100d00
	s_addc_u32 s47, s23, 0
	s_add_u32 s48, s22, 0x1c100e00
	s_addc_u32 s49, s23, 0
	s_add_u32 s50, s22, 0x1c100f00
	s_addc_u32 s51, s23, 0
	s_add_u32 s52, s22, 0x1c101000
	s_addc_u32 s53, s23, 0
	s_add_u32 s54, s22, 0x1c101100
	s_addc_u32 s55, s23, 0
	s_add_u32 s56, s22, 0x1c101200
	v_readlane_b32 s0, v255, 2
	s_addc_u32 s57, s23, 0
	s_mul_i32 s4, s27, s0
	s_add_u32 s58, s22, 0x1c101300
	s_mul_i32 s4, s4, s26
	s_addc_u32 s59, s23, 0
	s_mov_b32 s5, 1
	v_mov_b32_e32 v16, 0
	s_branch .LBB0_759

; DI unsigned xb_ld(unsigned* p)              { return __hip_atomic_load(p, __ATOMIC_RELAXED, __HIP_MEMORY_SCOPE_AGENT); }
; DI void xcd_barrier_complete(unsigned* bar, unsigned x, unsigned& nloc, unsigned& nx) {
;   const unsigned G = gridDim.x * gridDim.y * gridDim.z;
;   unsigned sum, cnt, mine, sp = 0u;
;   for (;;) {
;     sum = 0u; cnt = 0u; mine = 0u;
; #pragma unroll
;     for (unsigned j = 0; j < 16; ++j) { const unsigned c = xb_ld(&bar[XB_XCNT(j)]); sum += c; cnt += (c > 0u) ? 1u : 0u; mine = (j == x) ? c : mine; }
; DI void xcd_barrier(const XcdBarrier& b) {
;   asm volatile("s_waitcnt vmcnt(0)" ::: "memory");
;   __syncthreads();
;   if (threadIdx.x == 0) {
;     unsigned* bar = b.bar;
;     __builtin_amdgcn_s_waitcnt(0);
;     unsigned nloc = b.st[0], nx = b.st[1];
;     if (nloc == 0u) { xcd_barrier_complete(bar, b.x, nloc, nx); b.st[0] = nloc; b.st[1] = nx; }
.LBB0_884:
	s_or_b64 exec, exec, s[10:11]
	s_waitcnt vmcnt(0)
	v_readlane_b32 s0, v255, 5
	v_readlane_b32 s1, v255, 6
	s_barrier
	s_and_saveexec_b64 s[8:9], s[0:1]
	s_cbranch_execz .LBB0_936
	v_mov_b32_e32 v0, 0x12000
	s_waitcnt vmcnt(0) expcnt(0) lgkmcnt(0)
	ds_read_b32 v2, v0
	v_mov_b32_e32 v0, 0x12004
	ds_read_b32 v0, v0
	s_waitcnt lgkmcnt(1)
	v_cmp_ne_u32_e32 vcc, 0, v2
	s_cbranch_vccnz .LBB0_900
	s_add_u32 s10, s22, 0x1c100200
	s_addc_u32 s11, s23, 0
	s_add_u32 s12, s22, 0x1c100400
	s_addc_u32 s13, s23, 0
	s_add_u32 s14, s22, 0x1c100500
	s_addc_u32 s15, s23, 0
	s_add_u32 s16, s22, 0x1c100600
	s_addc_u32 s17, s23, 0
	s_add_u32 s18, s22, 0x1c100700
	s_addc_u32 s19, s23, 0
	s_add_u32 s28, s22, 0x1c100800
	s_addc_u32 s29, s23, 0
	s_add_u32 s40, s22, 0x1c100900
	s_addc_u32 s41, s23, 0
	s_add_u32 s42, s22, 0x1c100a00
	s_addc_u32 s43, s23, 0
	s_add_u32 s44, s22, 0x1c100b00
	s_addc_u32 s45, s23, 0
	s_add_u32 s46, s22, 0x1c100c00
	s_addc_u32 s47, s23, 0
	s_add_u32 s48, s22, 0x1c100d00
	s_addc_u32 s49, s23, 0
	s_add_u32 s50, s22, 0x1c100e00
	s_addc_u32 s51, s23, 0
	s_add_u32 s52, s22, 0x1c100f00
	s_addc_u32 s53, s23, 0
	s_add_u32 s54, s22, 0x1c101000
	s_addc_u32 s55, s23, 0
	s_add_u32 s56, s22, 0x1c101100
	s_addc_u32 s57, s23, 0
	s_add_u32 s58, s22, 0x1c101200
	v_readlane_b32 s0, v255, 2
	s_addc_u32 s59, s23, 0
	s_mul_i32 s4, s27, s0
	s_add_u32 s60, s22, 0x1c101300
	s_mul_i32 s4, s4, s26
	s_addc_u32 s61, s23, 0
	s_mov_b32 s5, 1
	v_mov_b32_e32 v16, 0
	s_branch .LBB0_888

; #define MFMA(a, b, c) __builtin_amdgcn_mfma_f32_32x32x16_bf16((a), (b), (c), 0, 0, 0)
; DI void gt_compute(const bf16* asr, const bf16* bsr, f32x16& acc0, f32x16& acc1, f32x16& acc2, f32x16& acc3) {
;   bf16x8 a[4], b0[4], b1[4], b2[4], b3[4];
; #pragma unroll
;   for (int kk = 0; kk < 4; ++kk) {
;     a[kk] = *(const bf16x8*)(asr + kk * 16);
;     b0[kk] = *(const bf16x8*)(bsr + kk * 16);
;     b1[kk] = *(const bf16x8*)(bsr + 32 * LDT + kk * 16);
;     b2[kk] = *(const bf16x8*)(bsr + 64 * LDT + kk * 16);
;     b3[kk] = *(const bf16x8*)(bsr + 96 * LDT + kk * 16);
;   }
;   __builtin_amdgcn_sched_barrier(0);
;   __builtin_amdgcn_s_setprio(2);
; #pragma unroll
;   for (int kk = 0; kk < 4; ++kk) {
;     acc0 = MFMA(a[kk], b0[kk], acc0); acc1 = MFMA(a[kk], b1[kk], acc1); acc2 = MFMA(a[kk], b2[kk], acc2); acc3 = MFMA(a[kk], b3[kk], acc3);
;   }
;   __builtin_amdgcn_s_setprio(0);
;   __builtin_amdgcn_sched_barrier(0);
; DI void gemm_mainloop(const bf16* __restrict__ A, int lda, const bf16* __restrict__ Bt, int ldb, int K, int m0, int n0,
;                       bf16* As, bf16* Bs, f32x16& acc0, f32x16& acc1, f32x16& acc2, f32x16& acc3) {
;     ...
;   for (int k0 = 0; k0 < K; k0 += 128) {
;     __syncthreads();
;     gt_store(t0, asw, bsw);
;     __syncthreads();
;     if (k0 + 128 < K) gt_load(t0, ap, bp, lda, ldb, KW(k0 + 128));
;     gt_compute(asr, bsr, acc0, acc1, acc2, acc3);
;     __syncthreads();
;     gt_store(t1, asw, bsw);
;     __syncthreads();
;     if (k0 + 192 < K) gt_load(t1, ap, bp, lda, ldb, KW(k0 + 192));
;     gt_compute(asr, bsr, acc0, acc1, acc2, acc3);
.LBB0_950:
	v_add_u32_e32 v152, 0x9000, v152
	v_add_u32_e32 v130, 0x9000, v130
	ds_read_b128 v[156:159], v152
	ds_read_b128 v[162:165], v152 offset:32
	ds_read_b128 v[174:177], v130 offset:18432
	ds_read_b128 v[178:181], v130 offset:18464
	ds_read_b128 v[182:185], v130 offset:23040
	ds_read_b128 v[186:189], v130 offset:23072
	ds_read_b128 v[190:193], v130 offset:27648
	ds_read_b128 v[194:197], v130 offset:27680
	ds_read_b128 v[198:201], v130 offset:32256
	ds_read_b128 v[202:205], v130 offset:32288
	ds_read_b128 v[206:209], v152 offset:64
	ds_read_b128 v[210:213], v152 offset:96
	ds_read_b128 v[214:217], v130 offset:18496
	ds_read_b128 v[226:229], v130 offset:18528
	ds_read_b128 v[230:233], v130 offset:23104
	ds_read_b128 v[234:237], v130 offset:23136
	ds_read_b128 v[238:241], v130 offset:27712
	ds_read_b128 v[242:245], v130 offset:27744
	ds_read_b128 v[246:249], v130 offset:32320
	ds_read_b128 v[250:253], v130 offset:32352
	v_add_u32_e32 v152, 0xffff7000, v152
	v_add_u32_e32 v130, 0xffff7000, v130
	s_setprio 2
	s_waitcnt lgkmcnt(14)
	v_mfma_f32_32x32x16_bf16 v[48:63], v[156:159], v[174:177], v[48:63]
	v_mfma_f32_32x32x16_bf16 v[16:31], v[156:159], v[182:185], v[16:31]
	s_waitcnt lgkmcnt(13)
	v_mfma_f32_32x32x16_bf16 v[32:47], v[156:159], v[190:193], v[32:47]
	s_waitcnt lgkmcnt(11)
	v_mfma_f32_32x32x16_bf16 v[0:15], v[156:159], v[198:201], v[0:15]
	v_mfma_f32_32x32x16_bf16 v[48:63], v[162:165], v[178:181], v[48:63]
	v_mfma_f32_32x32x16_bf16 v[16:31], v[162:165], v[186:189], v[16:31]
	v_mfma_f32_32x32x16_bf16 v[32:47], v[162:165], v[194:197], v[32:47]
	s_waitcnt lgkmcnt(10)
	v_mfma_f32_32x32x16_bf16 v[0:15], v[162:165], v[202:205], v[0:15]
	s_waitcnt lgkmcnt(7)
	v_mfma_f32_32x32x16_bf16 v[48:63], v[206:209], v[214:217], v[48:63]
	s_waitcnt lgkmcnt(5)
	v_mfma_f32_32x32x16_bf16 v[16:31], v[206:209], v[230:233], v[16:31]
	s_waitcnt lgkmcnt(3)
	v_mfma_f32_32x32x16_bf16 v[32:47], v[206:209], v[238:241], v[32:47]
	s_waitcnt lgkmcnt(1)
	v_mfma_f32_32x32x16_bf16 v[0:15], v[206:209], v[246:249], v[0:15]
	v_mfma_f32_32x32x16_bf16 v[48:63], v[210:213], v[226:229], v[48:63]
	v_mfma_f32_32x32x16_bf16 v[16:31], v[210:213], v[234:237], v[16:31]
	v_mfma_f32_32x32x16_bf16 v[32:47], v[210:213], v[242:245], v[32:47]
	s_waitcnt lgkmcnt(0)
	v_mfma_f32_32x32x16_bf16 v[0:15], v[210:213], v[250:253], v[0:15]
	s_setprio 0
	s_add_i32 s6, s50, 0xffffff80
	s_cmpk_lt_u32 s6, 0x380
	s_mov_b64 s[48:49], s[50:51]
	s_cbranch_scc0 .LBB0_955
.LBB0_951:
	s_add_u32 s50, s48, 0x80
	s_addc_u32 s51, s49, 0
	s_cmpk_gt_u32 s48, 0x37f
	s_waitcnt vmcnt(63) expcnt(7) lgkmcnt(15)
	s_waitcnt vmcnt(13)
	ds_write_b128 v150, v[72:75]
	ds_write_b128 v150, v[64:67] offset:4608
	ds_write_b128 v150, v[68:71] offset:9216
	s_waitcnt vmcnt(11)
	ds_write_b128 v150, v[80:83] offset:13824
	ds_write_b128 v150, v[76:79] offset:18432
	s_waitcnt vmcnt(10)
	ds_write_b128 v150, v[84:87] offset:23040
	s_waitcnt vmcnt(9)
	ds_write_b128 v150, v[96:99] offset:27648
	s_waitcnt vmcnt(8)
	ds_write_b128 v150, v[104:107] offset:32256
	s_waitcnt lgkmcnt(0)
	s_barrier
	s_cbranch_scc1 .LBB0_953
	s_cmp_lt_i32 s50, s30
	s_cselect_b32 s7, 0, -1
	s_cselect_b32 s6, 0, 0xfffffc00
	s_add_u32 s65, s28, s48
	s_addc_u32 s66, s29, s49
	s_add_u32 s6, s65, s6
	s_addc_u32 s7, s66, s7
	s_lshl_b64 s[6:7], s[6:7], 1
	v_lshl_add_u64 v[72:73], v[146:147], 0, s[6:7]
	v_add_co_u32_e32 v64, vcc, s59, v72
	v_lshl_add_u64 v[96:97], v[148:149], 0, s[6:7]
	s_nop 0
	v_addc_co_u32_e32 v65, vcc, 0, v73, vcc
	v_add_co_u32_e32 v68, vcc, 0x20000, v72
	s_nop 1
	v_addc_co_u32_e32 v69, vcc, 0, v73, vcc
	v_add_co_u32_e32 v80, vcc, 0x30000, v72
	global_load_dwordx4 v[64:67], v[64:65], off offset:256
	s_nop 0
	global_load_dwordx4 v[68:71], v[68:69], off offset:256
	v_addc_co_u32_e32 v81, vcc, 0, v73, vcc
	v_add_co_u32_e32 v84, vcc, 0x10000, v96
	global_load_dwordx4 v[72:75], v[72:73], off offset:256
	s_nop 0
	global_load_dwordx4 v[76:79], v[96:97], off offset:256
	v_addc_co_u32_e32 v85, vcc, 0, v97, vcc
	v_add_co_u32_e32 v98, vcc, 0x20000, v96
	global_load_dwordx4 v[80:83], v[80:81], off offset:256
	s_nop 0
	global_load_dwordx4 v[84:87], v[84:85], off offset:256
	v_addc_co_u32_e32 v99, vcc, 0, v97, vcc
	v_add_co_u32_e32 v104, vcc, 0x30000, v96
	s_nop 1
	v_addc_co_u32_e32 v105, vcc, 0, v97, vcc
	global_load_dwordx4 v[96:99], v[98:99], off offset:256
	s_nop 0
	global_load_dwordx4 v[104:107], v[104:105], off offset:256
; #define MFMA(a, b, c) __builtin_amdgcn_mfma_f32_32x32x16_bf16((a), (b), (c), 0, 0, 0)
; DI void gt_compute(const bf16* asr, const bf16* bsr, f32x16& acc0, f32x16& acc1, f32x16& acc2, f32x16& acc3) {
;   bf16x8 a[4], b0[4], b1[4], b2[4], b3[4];
; #pragma unroll
;   for (int kk = 0; kk < 4; ++kk) {
;     a[kk] = *(const bf16x8*)(asr + kk * 16);
;     b0[kk] = *(const bf16x8*)(bsr + kk * 16);
;     b1[kk] = *(const bf16x8*)(bsr + 32 * LDT + kk * 16);
;     b2[kk] = *(const bf16x8*)(bsr + 64 * LDT + kk * 16);
;     b3[kk] = *(const bf16x8*)(bsr + 96 * LDT + kk * 16);
;   }
;   __builtin_amdgcn_sched_barrier(0);
;   __builtin_amdgcn_s_setprio(2);
; #pragma unroll
;   for (int kk = 0; kk < 4; ++kk) {
;     acc0 = MFMA(a[kk], b0[kk], acc0); acc1 = MFMA(a[kk], b1[kk], acc1); acc2 = MFMA(a[kk], b2[kk], acc2); acc3 = MFMA(a[kk], b3[kk], acc3);
;   }
;   __builtin_amdgcn_s_setprio(0);
;   __builtin_amdgcn_sched_barrier(0);
; DI void gemm_mainloop(const bf16* __restrict__ A, int lda, const bf16* __restrict__ Bt, int ldb, int K, int m0, int n0,
;                       bf16* As, bf16* Bs, f32x16& acc0, f32x16& acc1, f32x16& acc2, f32x16& acc3) {
;     ...
;   for (int k0 = 0; k0 < K; k0 += 128) {
;     __syncthreads();
;     gt_store(t0, asw, bsw);
;     __syncthreads();
;     if (k0 + 128 < K) gt_load(t0, ap, bp, lda, ldb, KW(k0 + 128));
;     gt_compute(asr, bsr, acc0, acc1, acc2, acc3);
;     __syncthreads();
;     gt_store(t1, asw, bsw);
;     __syncthreads();
;     if (k0 + 192 < K) gt_load(t1, ap, bp, lda, ldb, KW(k0 + 192));
;     gt_compute(asr, bsr, acc0, acc1, acc2, acc3);
.LBB0_953:
	ds_read_b128 v[174:177], v152
	ds_read_b128 v[178:181], v152 offset:32
	ds_read_b128 v[182:185], v130 offset:18432
	ds_read_b128 v[186:189], v130 offset:18464
	ds_read_b128 v[190:193], v130 offset:23040
	ds_read_b128 v[194:197], v130 offset:23072
	ds_read_b128 v[198:201], v130 offset:27648
	ds_read_b128 v[202:205], v130 offset:27680
	ds_read_b128 v[206:209], v130 offset:32256
	ds_read_b128 v[210:213], v130 offset:32288
	ds_read_b128 v[214:217], v152 offset:64
	ds_read_b128 v[226:229], v152 offset:96
	ds_read_b128 v[230:233], v130 offset:18496
	ds_read_b128 v[234:237], v130 offset:18528
	ds_read_b128 v[238:241], v130 offset:23104
	ds_read_b128 v[242:245], v130 offset:23136
	ds_read_b128 v[246:249], v130 offset:27712
	ds_read_b128 v[250:253], v130 offset:27744
	ds_read_b128 v[156:159], v130 offset:32320
	ds_read_b128 v[162:165], v130 offset:32352
	s_setprio 2
	s_waitcnt lgkmcnt(14)
	v_mfma_f32_32x32x16_bf16 v[48:63], v[174:177], v[182:185], v[48:63]
	v_mfma_f32_32x32x16_bf16 v[16:31], v[174:177], v[190:193], v[16:31]
	s_waitcnt lgkmcnt(13)
	v_mfma_f32_32x32x16_bf16 v[32:47], v[174:177], v[198:201], v[32:47]
	s_waitcnt lgkmcnt(11)
	v_mfma_f32_32x32x16_bf16 v[0:15], v[174:177], v[206:209], v[0:15]
	v_mfma_f32_32x32x16_bf16 v[48:63], v[178:181], v[186:189], v[48:63]
	v_mfma_f32_32x32x16_bf16 v[16:31], v[178:181], v[194:197], v[16:31]
	v_mfma_f32_32x32x16_bf16 v[32:47], v[178:181], v[202:205], v[32:47]
	s_waitcnt lgkmcnt(10)
	v_mfma_f32_32x32x16_bf16 v[0:15], v[178:181], v[210:213], v[0:15]
	s_waitcnt lgkmcnt(7)
	v_mfma_f32_32x32x16_bf16 v[48:63], v[214:217], v[230:233], v[48:63]
	s_waitcnt lgkmcnt(5)
	v_mfma_f32_32x32x16_bf16 v[16:31], v[214:217], v[238:241], v[16:31]
	s_waitcnt lgkmcnt(3)
	v_mfma_f32_32x32x16_bf16 v[32:47], v[214:217], v[246:249], v[32:47]
	s_waitcnt lgkmcnt(1)
	v_mfma_f32_32x32x16_bf16 v[0:15], v[214:217], v[156:159], v[0:15]
	v_mfma_f32_32x32x16_bf16 v[48:63], v[226:229], v[234:237], v[48:63]
	v_mfma_f32_32x32x16_bf16 v[16:31], v[226:229], v[242:245], v[16:31]
	v_mfma_f32_32x32x16_bf16 v[32:47], v[226:229], v[250:253], v[32:47]
	s_waitcnt lgkmcnt(0)
	v_mfma_f32_32x32x16_bf16 v[0:15], v[226:229], v[162:165], v[0:15]
	s_setprio 0
	s_cmpk_gt_u32 s48, 0x33f
	v_add_u32_e32 v150, 0x9000, v150
	s_waitcnt vmcnt(5)
	ds_write_b128 v150, v[100:103]
	ds_write_b128 v150, v[88:91] offset:4608
	ds_write_b128 v150, v[92:95] offset:9216
	s_waitcnt vmcnt(3)
	ds_write_b128 v150, v[112:115] offset:13824
	ds_write_b128 v150, v[108:111] offset:18432
	s_waitcnt vmcnt(2)
	ds_write_b128 v150, v[116:119] offset:23040
	s_waitcnt vmcnt(1)
	ds_write_b128 v150, v[120:123] offset:27648
	s_waitcnt vmcnt(0)
	ds_write_b128 v150, v[124:127] offset:32256
	v_add_u32_e32 v150, 0xffff7000, v150
	s_waitcnt lgkmcnt(0)
	s_barrier
	s_cbranch_scc1 .LBB0_950
	s_cmp_lt_i32 s48, s31
	s_cselect_b32 s7, 0, -1
	s_cselect_b32 s6, 0, 0xfffffc00
	s_add_u32 s48, s28, s48
	s_addc_u32 s49, s29, s49
	s_add_u32 s6, s48, s6
	s_addc_u32 s7, s49, s7
	s_lshl_b64 s[6:7], s[6:7], 1
	v_lshl_add_u64 v[100:101], v[146:147], 0, s[6:7]
	v_add_co_u32_e32 v88, vcc, s59, v100
	v_lshl_add_u64 v[120:121], v[148:149], 0, s[6:7]
	s_nop 0
	v_addc_co_u32_e32 v89, vcc, 0, v101, vcc
	v_add_co_u32_e32 v92, vcc, 0x20000, v100
	s_nop 1
	v_addc_co_u32_e32 v93, vcc, 0, v101, vcc
	v_add_co_u32_e32 v112, vcc, 0x30000, v100
	global_load_dwordx4 v[88:91], v[88:89], off offset:384
	s_nop 0
	global_load_dwordx4 v[92:95], v[92:93], off offset:384
	v_addc_co_u32_e32 v113, vcc, 0, v101, vcc
	v_add_co_u32_e32 v116, vcc, 0x10000, v120
	global_load_dwordx4 v[100:103], v[100:101], off offset:384
	s_nop 0
	global_load_dwordx4 v[108:111], v[120:121], off offset:384
	v_addc_co_u32_e32 v117, vcc, 0, v121, vcc
	v_add_co_u32_e32 v122, vcc, 0x20000, v120
	global_load_dwordx4 v[112:115], v[112:113], off offset:384
	s_nop 0
	global_load_dwordx4 v[116:119], v[116:117], off offset:384
	v_addc_co_u32_e32 v123, vcc, 0, v121, vcc
	v_add_co_u32_e32 v124, vcc, 0x30000, v120
	s_nop 1
	v_addc_co_u32_e32 v125, vcc, 0, v121, vcc
	global_load_dwordx4 v[120:123], v[122:123], off offset:384
	s_nop 0
	global_load_dwordx4 v[124:127], v[124:125], off offset:384
	s_branch .LBB0_950

; DI unsigned xb_ld(unsigned* p)              { return __hip_atomic_load(p, __ATOMIC_RELAXED, __HIP_MEMORY_SCOPE_AGENT); }
; DI void xcd_barrier_complete(unsigned* bar, unsigned x, unsigned& nloc, unsigned& nx) {
;   const unsigned G = gridDim.x * gridDim.y * gridDim.z;
;   unsigned sum, cnt, mine, sp = 0u;
;   for (;;) {
;     sum = 0u; cnt = 0u; mine = 0u;
; #pragma unroll
;     for (unsigned j = 0; j < 16; ++j) { const unsigned c = xb_ld(&bar[XB_XCNT(j)]); sum += c; cnt += (c > 0u) ? 1u : 0u; mine = (j == x) ? c : mine; }
; DI void xcd_barrier(const XcdBarrier& b) {
;   asm volatile("s_waitcnt vmcnt(0)" ::: "memory");
;   __syncthreads();
;   if (threadIdx.x == 0) {
;     unsigned* bar = b.bar;
;     __builtin_amdgcn_s_waitcnt(0);
;     unsigned nloc = b.st[0], nx = b.st[1];
;     if (nloc == 0u) { xcd_barrier_complete(bar, b.x, nloc, nx); b.st[0] = nloc; b.st[1] = nx; }
.LBB0_1000:
	s_waitcnt vmcnt(0)
	v_readlane_b32 s0, v255, 5
	v_readlane_b32 s1, v255, 6
	s_barrier
	s_and_saveexec_b64 s[8:9], s[0:1]
	s_cbranch_execz .LBB0_1052
	v_mov_b32_e32 v0, 0x12000
	s_waitcnt vmcnt(0) expcnt(0) lgkmcnt(0)
	ds_read_b32 v2, v0
	v_mov_b32_e32 v0, 0x12004
	ds_read_b32 v0, v0
	s_waitcnt lgkmcnt(1)
	v_cmp_ne_u32_e32 vcc, 0, v2
	s_cbranch_vccnz .LBB0_1016
	s_add_u32 s10, s22, 0x1c100200
	s_addc_u32 s11, s23, 0
	s_add_u32 s12, s22, 0x1c100400
	s_addc_u32 s13, s23, 0
	s_add_u32 s14, s22, 0x1c100500
	s_addc_u32 s15, s23, 0
	s_add_u32 s16, s22, 0x1c100600
	s_addc_u32 s17, s23, 0
	s_add_u32 s18, s22, 0x1c100700
	s_addc_u32 s19, s23, 0
	s_add_u32 s28, s22, 0x1c100800
	s_addc_u32 s29, s23, 0
	s_add_u32 s40, s22, 0x1c100900
	s_addc_u32 s41, s23, 0
	s_add_u32 s42, s22, 0x1c100a00
	s_addc_u32 s43, s23, 0
	s_add_u32 s44, s22, 0x1c100b00
	s_addc_u32 s45, s23, 0
	s_add_u32 s46, s22, 0x1c100c00
	s_addc_u32 s47, s23, 0
	s_add_u32 s48, s22, 0x1c100d00
	s_addc_u32 s49, s23, 0
	s_add_u32 s50, s22, 0x1c100e00
	s_addc_u32 s51, s23, 0
	s_add_u32 s52, s22, 0x1c100f00
	s_addc_u32 s53, s23, 0
	s_add_u32 s54, s22, 0x1c101000
	s_addc_u32 s55, s23, 0
	s_add_u32 s56, s22, 0x1c101100
	s_addc_u32 s57, s23, 0
	s_add_u32 s58, s22, 0x1c101200
	v_readlane_b32 s0, v255, 2
	s_addc_u32 s59, s23, 0
	s_mul_i32 s4, s27, s0
	s_add_u32 s60, s22, 0x1c101300
	s_mul_i32 s4, s4, s26
	s_addc_u32 s61, s23, 0
	s_mov_b32 s5, 1
	v_mov_b32_e32 v16, 0
	s_branch .LBB0_1004

; DI unsigned xb_ld(unsigned* p)              { return __hip_atomic_load(p, __ATOMIC_RELAXED, __HIP_MEMORY_SCOPE_AGENT); }
; DI void xcd_barrier_complete(unsigned* bar, unsigned x, unsigned& nloc, unsigned& nx) {
;   const unsigned G = gridDim.x * gridDim.y * gridDim.z;
;   unsigned sum, cnt, mine, sp = 0u;
;   for (;;) {
;     sum = 0u; cnt = 0u; mine = 0u;
; #pragma unroll
;     for (unsigned j = 0; j < 16; ++j) { const unsigned c = xb_ld(&bar[XB_XCNT(j)]); sum += c; cnt += (c > 0u) ? 1u : 0u; mine = (j == x) ? c : mine; }
; DI void xcd_barrier(const XcdBarrier& b) {
;   asm volatile("s_waitcnt vmcnt(0)" ::: "memory");
;   __syncthreads();
;   if (threadIdx.x == 0) {
;     unsigned* bar = b.bar;
;     __builtin_amdgcn_s_waitcnt(0);
;     unsigned nloc = b.st[0], nx = b.st[1];
;     if (nloc == 0u) { xcd_barrier_complete(bar, b.x, nloc, nx); b.st[0] = nloc; b.st[1] = nx; }
.LBB0_1203:
	s_waitcnt vmcnt(0)
	v_readlane_b32 s0, v255, 5
	v_readlane_b32 s1, v255, 6
	s_barrier
	s_and_saveexec_b64 s[8:9], s[0:1]
	s_cbranch_execz .LBB0_1255
	v_mov_b32_e32 v0, 0x12000
	s_waitcnt vmcnt(0) expcnt(0) lgkmcnt(0)
	ds_read_b32 v2, v0
	v_mov_b32_e32 v0, 0x12004
	ds_read_b32 v0, v0
	s_waitcnt lgkmcnt(1)
	v_cmp_ne_u32_e32 vcc, 0, v2
	s_cbranch_vccnz .LBB0_1219
	s_add_u32 s10, s22, 0x1c100200
	s_addc_u32 s11, s23, 0
	s_add_u32 s12, s22, 0x1c100400
	s_addc_u32 s13, s23, 0
	s_add_u32 s14, s22, 0x1c100500
	s_addc_u32 s15, s23, 0
	s_add_u32 s16, s22, 0x1c100600
	s_addc_u32 s17, s23, 0
	s_add_u32 s18, s22, 0x1c100700
	s_addc_u32 s19, s23, 0
	s_add_u32 s20, s22, 0x1c100800
	s_addc_u32 s21, s23, 0
	s_add_u32 s28, s22, 0x1c100900
	s_addc_u32 s29, s23, 0
	s_add_u32 s40, s22, 0x1c100a00
	s_addc_u32 s41, s23, 0
	s_add_u32 s42, s22, 0x1c100b00
	s_addc_u32 s43, s23, 0
	s_add_u32 s44, s22, 0x1c100c00
	s_addc_u32 s45, s23, 0
	s_add_u32 s46, s22, 0x1c100d00
	s_addc_u32 s47, s23, 0
	s_add_u32 s48, s22, 0x1c100e00
	s_addc_u32 s49, s23, 0
	s_add_u32 s50, s22, 0x1c100f00
	s_addc_u32 s51, s23, 0
	s_add_u32 s52, s22, 0x1c101000
	s_addc_u32 s53, s23, 0
	s_add_u32 s54, s22, 0x1c101100
	s_addc_u32 s55, s23, 0
	s_add_u32 s56, s22, 0x1c101200
	v_readlane_b32 s0, v255, 2
	s_addc_u32 s57, s23, 0
	s_mul_i32 s4, s27, s0
	s_add_u32 s58, s22, 0x1c101300
	s_mul_i32 s4, s4, s26
	s_addc_u32 s59, s23, 0
	s_mov_b32 s5, 1
	v_mov_b32_e32 v16, 0
	s_branch .LBB0_1207

; #define MFMA(a, b, c) __builtin_amdgcn_mfma_f32_32x32x16_bf16((a), (b), (c), 0, 0, 0)
; DI void gt_compute(const bf16* asr, const bf16* bsr, f32x16& acc0, f32x16& acc1, f32x16& acc2, f32x16& acc3) {
;   bf16x8 a[4], b0[4], b1[4], b2[4], b3[4];
; #pragma unroll
;   for (int kk = 0; kk < 4; ++kk) {
;     a[kk] = *(const bf16x8*)(asr + kk * 16);
;     b0[kk] = *(const bf16x8*)(bsr + kk * 16);
;     b1[kk] = *(const bf16x8*)(bsr + 32 * LDT + kk * 16);
;     b2[kk] = *(const bf16x8*)(bsr + 64 * LDT + kk * 16);
;     b3[kk] = *(const bf16x8*)(bsr + 96 * LDT + kk * 16);
;   }
;   __builtin_amdgcn_sched_barrier(0);
;   __builtin_amdgcn_s_setprio(2);
; #pragma unroll
;   for (int kk = 0; kk < 4; ++kk) {
;     acc0 = MFMA(a[kk], b0[kk], acc0); acc1 = MFMA(a[kk], b1[kk], acc1); acc2 = MFMA(a[kk], b2[kk], acc2); acc3 = MFMA(a[kk], b3[kk], acc3);
;   }
;   __builtin_amdgcn_s_setprio(0);
;   __builtin_amdgcn_sched_barrier(0);
; DI void gemm_mainloop(const bf16* __restrict__ A, int lda, const bf16* __restrict__ Bt, int ldb, int K, int m0, int n0,
;                       bf16* As, bf16* Bs, f32x16& acc0, f32x16& acc1, f32x16& acc2, f32x16& acc3) {
;     ...
;   for (int k0 = 0; k0 < K; k0 += 128) {
;     __syncthreads();
;     gt_store(t0, asw, bsw);
;     __syncthreads();
;     if (k0 + 128 < K) gt_load(t0, ap, bp, lda, ldb, KW(k0 + 128));
;     gt_compute(asr, bsr, acc0, acc1, acc2, acc3);
;     __syncthreads();
;     gt_store(t1, asw, bsw);
;     __syncthreads();
;     if (k0 + 192 < K) gt_load(t1, ap, bp, lda, ldb, KW(k0 + 192));
;     gt_compute(asr, bsr, acc0, acc1, acc2, acc3);
.LBB0_1318:
	v_add_u32_e32 v138, 0x9000, v138
	v_add_u32_e32 v128, 0x9000, v128
	ds_read_b128 v[142:145], v138
	ds_read_b128 v[146:149], v138 offset:32
	ds_read_b128 v[150:153], v128 offset:18432
	ds_read_b128 v[154:157], v128 offset:18464
	ds_read_b128 v[162:165], v128 offset:23040
	ds_read_b128 v[166:169], v128 offset:23072
	ds_read_b128 v[170:173], v128 offset:27648
	ds_read_b128 v[174:177], v128 offset:27680
	ds_read_b128 v[178:181], v128 offset:32256
	ds_read_b128 v[182:185], v128 offset:32288
	ds_read_b128 v[186:189], v138 offset:64
	ds_read_b128 v[190:193], v138 offset:96
	ds_read_b128 v[194:197], v128 offset:18496
	ds_read_b128 v[198:201], v128 offset:18528
	ds_read_b128 v[202:205], v128 offset:23104
	ds_read_b128 v[206:209], v128 offset:23136
	ds_read_b128 v[210:213], v128 offset:27712
	ds_read_b128 v[214:217], v128 offset:27744
	ds_read_b128 v[226:229], v128 offset:32320
	ds_read_b128 v[230:233], v128 offset:32352
	v_add_u32_e32 v138, 0xffff7000, v138
	v_add_u32_e32 v128, 0xffff7000, v128
	s_setprio 2
	s_waitcnt lgkmcnt(14)
	v_mfma_f32_32x32x16_bf16 v[48:63], v[142:145], v[150:153], v[48:63]
	v_mfma_f32_32x32x16_bf16 v[32:47], v[142:145], v[162:165], v[32:47]
	s_waitcnt lgkmcnt(13)
	v_mfma_f32_32x32x16_bf16 v[16:31], v[142:145], v[170:173], v[16:31]
	s_waitcnt lgkmcnt(11)
	v_mfma_f32_32x32x16_bf16 v[0:15], v[142:145], v[178:181], v[0:15]
	v_mfma_f32_32x32x16_bf16 v[48:63], v[146:149], v[154:157], v[48:63]
	v_mfma_f32_32x32x16_bf16 v[32:47], v[146:149], v[166:169], v[32:47]
	v_mfma_f32_32x32x16_bf16 v[16:31], v[146:149], v[174:177], v[16:31]
	s_waitcnt lgkmcnt(10)
	v_mfma_f32_32x32x16_bf16 v[0:15], v[146:149], v[182:185], v[0:15]
	s_waitcnt lgkmcnt(7)
	v_mfma_f32_32x32x16_bf16 v[48:63], v[186:189], v[194:197], v[48:63]
	s_waitcnt lgkmcnt(5)
	v_mfma_f32_32x32x16_bf16 v[32:47], v[186:189], v[202:205], v[32:47]
	s_waitcnt lgkmcnt(3)
	v_mfma_f32_32x32x16_bf16 v[16:31], v[186:189], v[210:213], v[16:31]
	s_waitcnt lgkmcnt(1)
	v_mfma_f32_32x32x16_bf16 v[0:15], v[186:189], v[226:229], v[0:15]
	v_mfma_f32_32x32x16_bf16 v[48:63], v[190:193], v[198:201], v[48:63]
	v_mfma_f32_32x32x16_bf16 v[32:47], v[190:193], v[206:209], v[32:47]
	v_mfma_f32_32x32x16_bf16 v[16:31], v[190:193], v[214:217], v[16:31]
	s_waitcnt lgkmcnt(0)
	v_mfma_f32_32x32x16_bf16 v[0:15], v[190:193], v[230:233], v[0:15]
	s_setprio 0
	s_add_i32 s0, s16, 0xffffff80
	s_cmpk_lt_u32 s0, 0x380
	s_mov_b64 s[14:15], s[16:17]
	s_cbranch_scc0 .LBB0_1316
.LBB0_1319:
	s_add_u32 s16, s14, 0x80
	s_addc_u32 s17, s15, 0
	s_cmpk_gt_u32 s14, 0x37f
	s_waitcnt vmcnt(63) expcnt(7) lgkmcnt(15)
	s_waitcnt vmcnt(13)
	ds_write_b128 v136, v[72:75]
	ds_write_b128 v136, v[64:67] offset:4608
	ds_write_b128 v136, v[68:71] offset:9216
	s_waitcnt vmcnt(11)
	ds_write_b128 v136, v[80:83] offset:13824
	ds_write_b128 v136, v[76:79] offset:18432
	s_waitcnt vmcnt(10)
	ds_write_b128 v136, v[84:87] offset:23040
	s_waitcnt vmcnt(9)
	ds_write_b128 v136, v[96:99] offset:27648
	s_waitcnt vmcnt(8)
	ds_write_b128 v136, v[100:103] offset:32256
	s_waitcnt lgkmcnt(0)
	s_barrier
	s_cbranch_scc1 .LBB0_1321
	s_cmp_lt_i32 s16, s25
	s_cselect_b32 s0, 0, -1
	s_cselect_b32 s1, 0, 0xfffffc00
	s_add_u32 s6, s12, s14
	s_addc_u32 s7, s13, s15
	s_add_u32 s6, s6, s1
	s_addc_u32 s7, s7, s0
	s_lshl_b64 s[6:7], s[6:7], 1
	v_lshl_add_u64 v[72:73], v[132:133], 0, s[6:7]
	v_add_co_u32_e32 v64, vcc, s4, v72
	v_lshl_add_u64 v[96:97], v[134:135], 0, s[6:7]
	s_nop 0
	v_addc_co_u32_e32 v65, vcc, 0, v73, vcc
	v_add_co_u32_e32 v68, vcc, 0x20000, v72
	s_nop 1
	v_addc_co_u32_e32 v69, vcc, 0, v73, vcc
	v_add_co_u32_e32 v80, vcc, 0x30000, v72
	global_load_dwordx4 v[64:67], v[64:65], off offset:256
	s_nop 0
	global_load_dwordx4 v[68:71], v[68:69], off offset:256
	v_addc_co_u32_e32 v81, vcc, 0, v73, vcc
	v_add_co_u32_e32 v84, vcc, 0x10000, v96
	global_load_dwordx4 v[72:75], v[72:73], off offset:256
	s_nop 0
	global_load_dwordx4 v[76:79], v[96:97], off offset:256
	v_addc_co_u32_e32 v85, vcc, 0, v97, vcc
	v_add_co_u32_e32 v98, vcc, 0x20000, v96
	global_load_dwordx4 v[80:83], v[80:81], off offset:256
	s_nop 0
	global_load_dwordx4 v[84:87], v[84:85], off offset:256
	v_addc_co_u32_e32 v99, vcc, 0, v97, vcc
	v_add_co_u32_e32 v100, vcc, 0x30000, v96
	s_nop 1
	v_addc_co_u32_e32 v101, vcc, 0, v97, vcc
	global_load_dwordx4 v[96:99], v[98:99], off offset:256
	s_nop 0
	global_load_dwordx4 v[100:103], v[100:101], off offset:256
; #define MFMA(a, b, c) __builtin_amdgcn_mfma_f32_32x32x16_bf16((a), (b), (c), 0, 0, 0)
; DI void xcd_barrier(const XcdBarrier& b) {
;   asm volatile("s_waitcnt vmcnt(0)" ::: "memory");
;   __syncthreads();
;   if (threadIdx.x == 0) {
;     unsigned* bar = b.bar;
;     __builtin_amdgcn_s_waitcnt(0);
;     unsigned nloc = b.st[0], nx = b.st[1];
;     if (nloc == 0u) { xcd_barrier_complete(bar, b.x, nloc, nx); b.st[0] = nloc; b.st[1] = nx; }
; DI void gt_compute(const bf16* asr, const bf16* bsr, f32x16& acc0, f32x16& acc1, f32x16& acc2, f32x16& acc3) {
;   bf16x8 a[4], b0[4], b1[4], b2[4], b3[4];
; #pragma unroll
;   for (int kk = 0; kk < 4; ++kk) {
;     a[kk] = *(const bf16x8*)(asr + kk * 16);
;     b0[kk] = *(const bf16x8*)(bsr + kk * 16);
;     b1[kk] = *(const bf16x8*)(bsr + 32 * LDT + kk * 16);
;     b2[kk] = *(const bf16x8*)(bsr + 64 * LDT + kk * 16);
;     b3[kk] = *(const bf16x8*)(bsr + 96 * LDT + kk * 16);
;   }
;   __builtin_amdgcn_sched_barrier(0);
;   __builtin_amdgcn_s_setprio(2);
; #pragma unroll
;   for (int kk = 0; kk < 4; ++kk) {
;     acc0 = MFMA(a[kk], b0[kk], acc0); acc1 = MFMA(a[kk], b1[kk], acc1); acc2 = MFMA(a[kk], b2[kk], acc2); acc3 = MFMA(a[kk], b3[kk], acc3);
;   }
;   __builtin_amdgcn_s_setprio(0);
;   __builtin_amdgcn_sched_barrier(0);
; DI void gemm_mainloop(const bf16* __restrict__ A, int lda, const bf16* __restrict__ Bt, int ldb, int K, int m0, int n0,
;                       bf16* As, bf16* Bs, f32x16& acc0, f32x16& acc1, f32x16& acc2, f32x16& acc3) {
;     ...
;   for (int k0 = 0; k0 < K; k0 += 128) {
;     __syncthreads();
;     gt_store(t0, asw, bsw);
;     __syncthreads();
;     if (k0 + 128 < K) gt_load(t0, ap, bp, lda, ldb, KW(k0 + 128));
;     gt_compute(asr, bsr, acc0, acc1, acc2, acc3);
;     __syncthreads();
;     gt_store(t1, asw, bsw);
;     __syncthreads();
;     if (k0 + 192 < K) gt_load(t1, ap, bp, lda, ldb, KW(k0 + 192));
;     gt_compute(asr, bsr, acc0, acc1, acc2, acc3);
.LBB0_1321:
	ds_read_b128 v[142:145], v138
	ds_read_b128 v[146:149], v138 offset:32
	ds_read_b128 v[150:153], v128 offset:18432
	ds_read_b128 v[154:157], v128 offset:18464
	ds_read_b128 v[162:165], v128 offset:23040
	ds_read_b128 v[166:169], v128 offset:23072
	ds_read_b128 v[170:173], v128 offset:27648
	ds_read_b128 v[174:177], v128 offset:27680
	ds_read_b128 v[178:181], v128 offset:32256
	ds_read_b128 v[182:185], v128 offset:32288
	ds_read_b128 v[186:189], v138 offset:64
	ds_read_b128 v[190:193], v138 offset:96
	ds_read_b128 v[194:197], v128 offset:18496
	ds_read_b128 v[198:201], v128 offset:18528
	ds_read_b128 v[202:205], v128 offset:23104
	ds_read_b128 v[206:209], v128 offset:23136
	ds_read_b128 v[210:213], v128 offset:27712
	ds_read_b128 v[214:217], v128 offset:27744
	ds_read_b128 v[226:229], v128 offset:32320
	ds_read_b128 v[230:233], v128 offset:32352
	s_setprio 2
	s_waitcnt lgkmcnt(14)
	v_mfma_f32_32x32x16_bf16 v[48:63], v[142:145], v[150:153], v[48:63]
	v_mfma_f32_32x32x16_bf16 v[32:47], v[142:145], v[162:165], v[32:47]
	s_waitcnt lgkmcnt(13)
	v_mfma_f32_32x32x16_bf16 v[16:31], v[142:145], v[170:173], v[16:31]
	s_waitcnt lgkmcnt(11)
	v_mfma_f32_32x32x16_bf16 v[0:15], v[142:145], v[178:181], v[0:15]
	v_mfma_f32_32x32x16_bf16 v[48:63], v[146:149], v[154:157], v[48:63]
	v_mfma_f32_32x32x16_bf16 v[32:47], v[146:149], v[166:169], v[32:47]
	v_mfma_f32_32x32x16_bf16 v[16:31], v[146:149], v[174:177], v[16:31]
	s_waitcnt lgkmcnt(10)
	v_mfma_f32_32x32x16_bf16 v[0:15], v[146:149], v[182:185], v[0:15]
	s_waitcnt lgkmcnt(7)
	v_mfma_f32_32x32x16_bf16 v[48:63], v[186:189], v[194:197], v[48:63]
	s_waitcnt lgkmcnt(5)
	v_mfma_f32_32x32x16_bf16 v[32:47], v[186:189], v[202:205], v[32:47]
	s_waitcnt lgkmcnt(3)
	v_mfma_f32_32x32x16_bf16 v[16:31], v[186:189], v[210:213], v[16:31]
	s_waitcnt lgkmcnt(1)
	v_mfma_f32_32x32x16_bf16 v[0:15], v[186:189], v[226:229], v[0:15]
	v_mfma_f32_32x32x16_bf16 v[48:63], v[190:193], v[198:201], v[48:63]
	v_mfma_f32_32x32x16_bf16 v[32:47], v[190:193], v[206:209], v[32:47]
	v_mfma_f32_32x32x16_bf16 v[16:31], v[190:193], v[214:217], v[16:31]
	s_waitcnt lgkmcnt(0)
	v_mfma_f32_32x32x16_bf16 v[0:15], v[190:193], v[230:233], v[0:15]
	s_setprio 0
	s_cmpk_gt_u32 s14, 0x33f
	v_add_u32_e32 v136, 0x9000, v136
	s_waitcnt vmcnt(5)
	ds_write_b128 v136, v[104:107]
	ds_write_b128 v136, v[88:91] offset:4608
	ds_write_b128 v136, v[92:95] offset:9216
	s_waitcnt vmcnt(3)
	ds_write_b128 v136, v[112:115] offset:13824
	ds_write_b128 v136, v[108:111] offset:18432
	s_waitcnt vmcnt(2)
	ds_write_b128 v136, v[116:119] offset:23040
	s_waitcnt vmcnt(1)
	ds_write_b128 v136, v[120:123] offset:27648
	s_waitcnt vmcnt(0)
	ds_write_b128 v136, v[124:127] offset:32256
	v_add_u32_e32 v136, 0xffff7000, v136
	s_waitcnt lgkmcnt(0)
	s_barrier
	s_cbranch_scc1 .LBB0_1318
	s_cmp_lt_i32 s14, s28
	s_cselect_b32 s0, 0, -1
	s_cselect_b32 s1, 0, 0xfffffc00
	s_add_u32 s6, s12, s14
	s_addc_u32 s7, s13, s15
	s_add_u32 s6, s6, s1
	s_addc_u32 s7, s7, s0
	s_lshl_b64 s[6:7], s[6:7], 1
	v_lshl_add_u64 v[104:105], v[132:133], 0, s[6:7]
	v_add_co_u32_e32 v88, vcc, s4, v104
	v_lshl_add_u64 v[120:121], v[134:135], 0, s[6:7]
	s_nop 0
	v_addc_co_u32_e32 v89, vcc, 0, v105, vcc
	v_add_co_u32_e32 v92, vcc, 0x20000, v104
	s_nop 1
	v_addc_co_u32_e32 v93, vcc, 0, v105, vcc
	v_add_co_u32_e32 v112, vcc, 0x30000, v104
	global_load_dwordx4 v[88:91], v[88:89], off offset:384
	s_nop 0
	global_load_dwordx4 v[92:95], v[92:93], off offset:384
	v_addc_co_u32_e32 v113, vcc, 0, v105, vcc
	v_add_co_u32_e32 v116, vcc, 0x10000, v120
	global_load_dwordx4 v[104:107], v[104:105], off offset:384
	s_nop 0
	global_load_dwordx4 v[108:111], v[120:121], off offset:384
	v_addc_co_u32_e32 v117, vcc, 0, v121, vcc
	v_add_co_u32_e32 v122, vcc, 0x20000, v120
	global_load_dwordx4 v[112:115], v[112:113], off offset:384
	s_nop 0
	global_load_dwordx4 v[116:119], v[116:117], off offset:384
	v_addc_co_u32_e32 v123, vcc, 0, v121, vcc
	v_add_co_u32_e32 v124, vcc, 0x30000, v120
	s_nop 1
	v_addc_co_u32_e32 v125, vcc, 0, v121, vcc
	global_load_dwordx4 v[120:123], v[122:123], off offset:384
	s_nop 0
	global_load_dwordx4 v[124:127], v[124:125], off offset:384
	s_branch .LBB0_1318
.LBB0_1323:
	s_waitcnt vmcnt(0)
	v_readlane_b32 s0, v255, 5
	v_readlane_b32 s1, v255, 6
	s_waitcnt vmcnt(63) expcnt(7) lgkmcnt(15)
	s_barrier
	s_and_saveexec_b64 s[8:9], s[0:1]
	s_cbranch_execz .LBB0_1375
	v_mov_b32_e32 v0, 0x12000
	s_waitcnt vmcnt(0) expcnt(0) lgkmcnt(0)
	ds_read_b32 v2, v0
	v_mov_b32_e32 v0, 0x12004
	ds_read_b32 v0, v0
	s_waitcnt lgkmcnt(1)
	v_cmp_ne_u32_e32 vcc, 0, v2
	s_cbranch_vccnz .LBB0_1339
	s_add_u32 s10, s22, 0x1c100200
	s_addc_u32 s11, s23, 0
	s_add_u32 s12, s22, 0x1c100400
	s_addc_u32 s13, s23, 0
	s_add_u32 s14, s22, 0x1c100500
	s_addc_u32 s15, s23, 0
	s_add_u32 s16, s22, 0x1c100600
	s_addc_u32 s17, s23, 0
	s_add_u32 s18, s22, 0x1c100700
	s_addc_u32 s19, s23, 0
	s_add_u32 s20, s22, 0x1c100800
	s_addc_u32 s21, s23, 0
	s_add_u32 s28, s22, 0x1c100900
	s_addc_u32 s29, s23, 0
	s_add_u32 s36, s22, 0x1c100a00
	s_addc_u32 s37, s23, 0
	s_add_u32 s40, s22, 0x1c100b00
	s_addc_u32 s41, s23, 0
	s_add_u32 s42, s22, 0x1c100c00
	s_addc_u32 s43, s23, 0
	s_add_u32 s44, s22, 0x1c100d00
	s_addc_u32 s45, s23, 0
	s_add_u32 s46, s22, 0x1c100e00
	s_addc_u32 s47, s23, 0
	s_add_u32 s48, s22, 0x1c100f00
	s_addc_u32 s49, s23, 0
	s_add_u32 s50, s22, 0x1c101000
	s_addc_u32 s51, s23, 0
	s_add_u32 s52, s22, 0x1c101100
	s_addc_u32 s53, s23, 0
	s_add_u32 s54, s22, 0x1c101200
	v_readlane_b32 s0, v255, 2
	s_addc_u32 s55, s23, 0
	s_mul_i32 s4, s27, s0
	s_add_u32 s56, s22, 0x1c101300
	s_mul_i32 s4, s4, s26
	s_addc_u32 s57, s23, 0
	s_mov_b32 s5, 1
	v_mov_b32_e32 v16, 0
	s_branch .LBB0_1327

; DI unsigned xb_ld(unsigned* p)              { return __hip_atomic_load(p, __ATOMIC_RELAXED, __HIP_MEMORY_SCOPE_AGENT); }
; DI void xcd_barrier_complete(unsigned* bar, unsigned x, unsigned& nloc, unsigned& nx) {
;   const unsigned G = gridDim.x * gridDim.y * gridDim.z;
;   unsigned sum, cnt, mine, sp = 0u;
;   for (;;) {
;     sum = 0u; cnt = 0u; mine = 0u;
; #pragma unroll
;     for (unsigned j = 0; j < 16; ++j) { const unsigned c = xb_ld(&bar[XB_XCNT(j)]); sum += c; cnt += (c > 0u) ? 1u : 0u; mine = (j == x) ? c : mine; }
; DI void xcd_barrier(const XcdBarrier& b) {
;   asm volatile("s_waitcnt vmcnt(0)" ::: "memory");
;   __syncthreads();
;   if (threadIdx.x == 0) {
;     unsigned* bar = b.bar;
;     __builtin_amdgcn_s_waitcnt(0);
;     unsigned nloc = b.st[0], nx = b.st[1];
;     if (nloc == 0u) { xcd_barrier_complete(bar, b.x, nloc, nx); b.st[0] = nloc; b.st[1] = nx; }
.LBB0_1378:
	s_or_b64 exec, exec, s[10:11]
	s_waitcnt vmcnt(0)
	v_readlane_b32 s0, v255, 5
	v_readlane_b32 s1, v255, 6
	s_barrier
	s_and_saveexec_b64 s[8:9], s[0:1]
	s_cbranch_execz .LBB0_1430
	v_mov_b32_e32 v0, 0x12000
	s_waitcnt vmcnt(0) expcnt(0) lgkmcnt(0)
	ds_read_b32 v2, v0
	v_mov_b32_e32 v0, 0x12004
	ds_read_b32 v0, v0
	s_waitcnt lgkmcnt(1)
	v_cmp_ne_u32_e32 vcc, 0, v2
	s_cbranch_vccnz .LBB0_1394
	s_add_u32 s10, s22, 0x1c100200
	s_addc_u32 s11, s23, 0
	s_add_u32 s12, s22, 0x1c100400
	s_addc_u32 s13, s23, 0
	s_add_u32 s14, s22, 0x1c100500
	s_addc_u32 s15, s23, 0
	s_add_u32 s16, s22, 0x1c100600
	s_addc_u32 s17, s23, 0
	s_add_u32 s18, s22, 0x1c100700
	s_addc_u32 s19, s23, 0
	s_add_u32 s20, s22, 0x1c100800
	s_addc_u32 s21, s23, 0
	s_add_u32 s28, s22, 0x1c100900
	s_addc_u32 s29, s23, 0
	s_add_u32 s36, s22, 0x1c100a00
	s_addc_u32 s37, s23, 0
	s_add_u32 s38, s22, 0x1c100b00
	s_addc_u32 s39, s23, 0
	s_add_u32 s40, s22, 0x1c100c00
	s_addc_u32 s41, s23, 0
	s_add_u32 s42, s22, 0x1c100d00
	s_addc_u32 s43, s23, 0
	s_add_u32 s44, s22, 0x1c100e00
	s_addc_u32 s45, s23, 0
	s_add_u32 s46, s22, 0x1c100f00
	s_addc_u32 s47, s23, 0
	s_add_u32 s48, s22, 0x1c101000
	s_addc_u32 s49, s23, 0
	s_add_u32 s50, s22, 0x1c101100
	s_addc_u32 s51, s23, 0
	s_add_u32 s52, s22, 0x1c101200
	v_readlane_b32 s0, v255, 2
	s_addc_u32 s53, s23, 0
	s_mul_i32 s4, s27, s0
	s_add_u32 s54, s22, 0x1c101300
	s_mul_i32 s4, s4, s26
	s_addc_u32 s55, s23, 0
	s_mov_b32 s5, 1
	v_mov_b32_e32 v16, 0
	s_branch .LBB0_1382

; DI unsigned xb_ld(unsigned* p)              { return __hip_atomic_load(p, __ATOMIC_RELAXED, __HIP_MEMORY_SCOPE_AGENT); }
; DI void xcd_barrier_complete(unsigned* bar, unsigned x, unsigned& nloc, unsigned& nx) {
;   const unsigned G = gridDim.x * gridDim.y * gridDim.z;
;   unsigned sum, cnt, mine, sp = 0u;
;   for (;;) {
;     sum = 0u; cnt = 0u; mine = 0u;
; #pragma unroll
;     for (unsigned j = 0; j < 16; ++j) { const unsigned c = xb_ld(&bar[XB_XCNT(j)]); sum += c; cnt += (c > 0u) ? 1u : 0u; mine = (j == x) ? c : mine; }
; DI void xcd_barrier(const XcdBarrier& b) {
;   asm volatile("s_waitcnt vmcnt(0)" ::: "memory");
;   __syncthreads();
;   if (threadIdx.x == 0) {
;     unsigned* bar = b.bar;
;     __builtin_amdgcn_s_waitcnt(0);
;     unsigned nloc = b.st[0], nx = b.st[1];
;     if (nloc == 0u) { xcd_barrier_complete(bar, b.x, nloc, nx); b.st[0] = nloc; b.st[1] = nx; }
.LBB0_1445:
	s_waitcnt vmcnt(0)
	s_barrier
	s_mov_b64 s[6:7], exec
	v_readlane_b32 s0, v255, 5
	v_readlane_b32 s1, v255, 6
	s_and_b64 s[0:1], s[6:7], s[0:1]
	s_mov_b64 exec, s[0:1]
	s_cbranch_execz .LBB0_1497
	v_mov_b32_e32 v0, 0x12000
	s_waitcnt vmcnt(0) expcnt(0) lgkmcnt(0)
	ds_read_b32 v2, v0
	v_mov_b32_e32 v0, 0x12004
	ds_read_b32 v0, v0
	s_waitcnt lgkmcnt(1)
	v_cmp_ne_u32_e32 vcc, 0, v2
	s_cbranch_vccnz .LBB0_1461
	s_add_u32 s8, s22, 0x1c100200
	s_addc_u32 s9, s23, 0
	s_add_u32 s10, s22, 0x1c100400
	s_addc_u32 s11, s23, 0
	s_add_u32 s12, s22, 0x1c100500
	s_addc_u32 s13, s23, 0
	s_add_u32 s14, s22, 0x1c100600
	s_addc_u32 s15, s23, 0
	s_add_u32 s16, s22, 0x1c100700
	s_addc_u32 s17, s23, 0
	s_add_u32 s18, s22, 0x1c100800
	s_addc_u32 s19, s23, 0
	s_add_u32 s20, s22, 0x1c100900
	s_addc_u32 s21, s23, 0
	s_add_u32 s28, s22, 0x1c100a00
	s_addc_u32 s29, s23, 0
	s_add_u32 s36, s22, 0x1c100b00
	s_addc_u32 s37, s23, 0
	s_add_u32 s38, s22, 0x1c100c00
	s_addc_u32 s39, s23, 0
	s_add_u32 s40, s22, 0x1c100d00
	s_addc_u32 s41, s23, 0
	s_add_u32 s42, s22, 0x1c100e00
	s_addc_u32 s43, s23, 0
	s_add_u32 s44, s22, 0x1c100f00
	s_addc_u32 s45, s23, 0
	s_add_u32 s46, s22, 0x1c101000
	s_addc_u32 s47, s23, 0
	s_add_u32 s48, s22, 0x1c101100
	s_addc_u32 s49, s23, 0
	s_add_u32 s50, s22, 0x1c101200
	v_readlane_b32 s0, v255, 2
	s_addc_u32 s51, s23, 0
	s_mul_i32 s0, s27, s0
	s_add_u32 s52, s22, 0x1c101300
	s_mul_i32 s0, s0, s26
	s_addc_u32 s53, s23, 0
	s_mov_b32 s1, 1
	v_mov_b32_e32 v16, 0
	s_branch .LBB0_1449

; DI unsigned xb_ld(unsigned* p)              { return __hip_atomic_load(p, __ATOMIC_RELAXED, __HIP_MEMORY_SCOPE_AGENT); }
; DI void xcd_barrier_complete(unsigned* bar, unsigned x, unsigned& nloc, unsigned& nx) {
;   const unsigned G = gridDim.x * gridDim.y * gridDim.z;
;   unsigned sum, cnt, mine, sp = 0u;
;   for (;;) {
;     sum = 0u; cnt = 0u; mine = 0u;
; #pragma unroll
;     for (unsigned j = 0; j < 16; ++j) { const unsigned c = xb_ld(&bar[XB_XCNT(j)]); sum += c; cnt += (c > 0u) ? 1u : 0u; mine = (j == x) ? c : mine; }
; DI void xcd_barrier(const XcdBarrier& b) {
;   asm volatile("s_waitcnt vmcnt(0)" ::: "memory");
;   __syncthreads();
;   if (threadIdx.x == 0) {
;     unsigned* bar = b.bar;
;     __builtin_amdgcn_s_waitcnt(0);
;     unsigned nloc = b.st[0], nx = b.st[1];
;     if (nloc == 0u) { xcd_barrier_complete(bar, b.x, nloc, nx); b.st[0] = nloc; b.st[1] = nx; }
.LBB0_1519:
	s_waitcnt vmcnt(0)
	s_barrier
	s_mov_b64 s[6:7], exec
	v_readlane_b32 s0, v255, 5
	v_readlane_b32 s1, v255, 6
	v_readlane_b32 s2, v255, 0
	s_and_b64 s[0:1], s[6:7], s[0:1]
	v_readlane_b32 s3, v255, 1
	s_mov_b64 exec, s[0:1]
	s_cbranch_execz .LBB0_1571
	v_mov_b32_e32 v0, 0x12000
	s_waitcnt vmcnt(0) expcnt(0) lgkmcnt(0)
	ds_read_b32 v2, v0
	v_mov_b32_e32 v0, 0x12004
	ds_read_b32 v0, v0
	s_waitcnt lgkmcnt(1)
	v_cmp_ne_u32_e32 vcc, 0, v2
	s_cbranch_vccnz .LBB0_1535
	s_add_u32 s8, s22, 0x1c100200
	s_addc_u32 s9, s23, 0
	s_add_u32 s10, s22, 0x1c100400
	s_addc_u32 s11, s23, 0
	s_add_u32 s12, s22, 0x1c100500
	s_addc_u32 s13, s23, 0
	s_add_u32 s14, s22, 0x1c100600
	s_addc_u32 s15, s23, 0
	s_add_u32 s16, s22, 0x1c100700
	s_addc_u32 s17, s23, 0
	s_add_u32 s18, s22, 0x1c100800
	s_addc_u32 s19, s23, 0
	s_add_u32 s20, s22, 0x1c100900
	s_addc_u32 s21, s23, 0
	s_add_u32 s28, s22, 0x1c100a00
	s_addc_u32 s29, s23, 0
	s_add_u32 s36, s22, 0x1c100b00
	s_addc_u32 s37, s23, 0
	s_add_u32 s38, s22, 0x1c100c00
	s_addc_u32 s39, s23, 0
	s_add_u32 s40, s22, 0x1c100d00
	s_addc_u32 s41, s23, 0
	s_add_u32 s42, s22, 0x1c100e00
	s_addc_u32 s43, s23, 0
	s_add_u32 s44, s22, 0x1c100f00
	s_addc_u32 s45, s23, 0
	s_add_u32 s46, s22, 0x1c101000
	s_addc_u32 s47, s23, 0
	s_add_u32 s48, s22, 0x1c101100
	s_addc_u32 s49, s23, 0
	s_add_u32 s50, s22, 0x1c101200
	v_readlane_b32 s0, v255, 2
	s_addc_u32 s51, s23, 0
	s_mul_i32 s0, s27, s0
	s_add_u32 s52, s22, 0x1c101300
	s_mul_i32 s0, s0, s26
	s_addc_u32 s53, s23, 0
	s_mov_b32 s1, 1
	v_mov_b32_e32 v16, 0
	s_branch .LBB0_1523

; DI unsigned xb_ld(unsigned* p)              { return __hip_atomic_load(p, __ATOMIC_RELAXED, __HIP_MEMORY_SCOPE_AGENT); }
; DI void xcd_barrier_complete(unsigned* bar, unsigned x, unsigned& nloc, unsigned& nx) {
;   const unsigned G = gridDim.x * gridDim.y * gridDim.z;
;   unsigned sum, cnt, mine, sp = 0u;
;   for (;;) {
;     sum = 0u; cnt = 0u; mine = 0u;
; #pragma unroll
;     for (unsigned j = 0; j < 16; ++j) { const unsigned c = xb_ld(&bar[XB_XCNT(j)]); sum += c; cnt += (c > 0u) ? 1u : 0u; mine = (j == x) ? c : mine; }
; DI void xcd_barrier(const XcdBarrier& b) {
;   asm volatile("s_waitcnt vmcnt(0)" ::: "memory");
;   __syncthreads();
;   if (threadIdx.x == 0) {
;     unsigned* bar = b.bar;
;     __builtin_amdgcn_s_waitcnt(0);
;     unsigned nloc = b.st[0], nx = b.st[1];
;     if (nloc == 0u) { xcd_barrier_complete(bar, b.x, nloc, nx); b.st[0] = nloc; b.st[1] = nx; }
.LBB0_1578:
	s_or_b64 exec, exec, s[6:7]
	s_waitcnt vmcnt(0)
	s_barrier
	s_mov_b64 s[2:3], exec
	v_readlane_b32 s0, v255, 5
	v_readlane_b32 s1, v255, 6
	s_and_b64 s[0:1], s[2:3], s[0:1]
	s_mov_b64 exec, s[0:1]
	s_cbranch_execz .LBB0_1630
	v_mov_b32_e32 v0, 0x12000
	s_waitcnt vmcnt(0) expcnt(0) lgkmcnt(0)
	ds_read_b32 v2, v0
	v_mov_b32_e32 v0, 0x12004
	ds_read_b32 v0, v0
	s_waitcnt lgkmcnt(1)
	v_cmp_ne_u32_e32 vcc, 0, v2
	s_cbranch_vccnz .LBB0_1594
	s_add_u32 s6, s22, 0x1c100200
	s_addc_u32 s7, s23, 0
	s_add_u32 s8, s22, 0x1c100400
	s_addc_u32 s9, s23, 0
	s_add_u32 s10, s22, 0x1c100500
	s_addc_u32 s11, s23, 0
	s_add_u32 s12, s22, 0x1c100600
	s_addc_u32 s13, s23, 0
	s_add_u32 s14, s22, 0x1c100700
	s_addc_u32 s15, s23, 0
	s_add_u32 s16, s22, 0x1c100800
	s_addc_u32 s17, s23, 0
	s_add_u32 s18, s22, 0x1c100900
	s_addc_u32 s19, s23, 0
	s_add_u32 s20, s22, 0x1c100a00
	s_addc_u32 s21, s23, 0
	s_add_u32 s28, s22, 0x1c100b00
	s_addc_u32 s29, s23, 0
	s_add_u32 s36, s22, 0x1c100c00
	s_addc_u32 s37, s23, 0
	s_add_u32 s38, s22, 0x1c100d00
	s_addc_u32 s39, s23, 0
	s_add_u32 s40, s22, 0x1c100e00
	s_addc_u32 s41, s23, 0
	s_add_u32 s42, s22, 0x1c100f00
	s_addc_u32 s43, s23, 0
	s_add_u32 s44, s22, 0x1c101000
	s_addc_u32 s45, s23, 0
	s_add_u32 s46, s22, 0x1c101100
	s_addc_u32 s47, s23, 0
	s_add_u32 s48, s22, 0x1c101200
	v_readlane_b32 s0, v255, 2
	s_addc_u32 s49, s23, 0
	s_mul_i32 s0, s27, s0
	s_add_u32 s50, s22, 0x1c101300
	s_mul_i32 s0, s0, s26
	s_addc_u32 s51, s23, 0
	s_mov_b32 s1, 1
	v_mov_b32_e32 v16, 0
	s_branch .LBB0_1582

; DI unsigned xb_ld(unsigned* p)              { return __hip_atomic_load(p, __ATOMIC_RELAXED, __HIP_MEMORY_SCOPE_AGENT); }
; DI void xcd_barrier_complete(unsigned* bar, unsigned x, unsigned& nloc, unsigned& nx) {
;   const unsigned G = gridDim.x * gridDim.y * gridDim.z;
;   unsigned sum, cnt, mine, sp = 0u;
;   for (;;) {
;     sum = 0u; cnt = 0u; mine = 0u;
; #pragma unroll
;     for (unsigned j = 0; j < 16; ++j) { const unsigned c = xb_ld(&bar[XB_XCNT(j)]); sum += c; cnt += (c > 0u) ? 1u : 0u; mine = (j == x) ? c : mine; }
; DI void xcd_barrier(const XcdBarrier& b) {
;   asm volatile("s_waitcnt vmcnt(0)" ::: "memory");
;   __syncthreads();
;   if (threadIdx.x == 0) {
;     unsigned* bar = b.bar;
;     __builtin_amdgcn_s_waitcnt(0);
;     unsigned nloc = b.st[0], nx = b.st[1];
;     if (nloc == 0u) { xcd_barrier_complete(bar, b.x, nloc, nx); b.st[0] = nloc; b.st[1] = nx; }
.LBB0_1652:
	s_waitcnt vmcnt(0)
	s_barrier
	s_mov_b64 s[2:3], exec
	v_readlane_b32 s0, v255, 5
	v_readlane_b32 s1, v255, 6
	s_and_b64 s[0:1], s[2:3], s[0:1]
	s_mov_b64 exec, s[0:1]
	s_cbranch_execz .LBB0_1704
	v_mov_b32_e32 v0, 0x12000
	s_waitcnt vmcnt(0) expcnt(0) lgkmcnt(0)
	ds_read_b32 v2, v0
	v_mov_b32_e32 v0, 0x12004
	ds_read_b32 v0, v0
	s_waitcnt lgkmcnt(1)
	v_cmp_ne_u32_e32 vcc, 0, v2
	s_cbranch_vccnz .LBB0_1668
	s_add_u32 s4, s22, 0x1c100200
	s_addc_u32 s5, s23, 0
	s_add_u32 s6, s22, 0x1c100400
	s_addc_u32 s7, s23, 0
	s_add_u32 s8, s22, 0x1c100500
	s_addc_u32 s9, s23, 0
	s_add_u32 s10, s22, 0x1c100600
	s_addc_u32 s11, s23, 0
	s_add_u32 s12, s22, 0x1c100700
	s_addc_u32 s13, s23, 0
	s_add_u32 s14, s22, 0x1c100800
	s_addc_u32 s15, s23, 0
	s_add_u32 s16, s22, 0x1c100900
	s_addc_u32 s17, s23, 0
	s_add_u32 s18, s22, 0x1c100a00
	s_addc_u32 s19, s23, 0
	v_readlane_b32 s0, v255, 2
	s_add_u32 s20, s22, 0x1c100b00
	s_mul_i32 s0, s27, s0
	s_addc_u32 s21, s23, 0
	s_mul_i32 s0, s0, s26
	s_add_u32 s26, s22, 0x1c100c00
	s_addc_u32 s27, s23, 0
	s_add_u32 s28, s22, 0x1c100d00
	s_addc_u32 s29, s23, 0
	s_add_u32 s36, s22, 0x1c100e00
	s_addc_u32 s37, s23, 0
	s_add_u32 s38, s22, 0x1c100f00
	s_addc_u32 s39, s23, 0
	s_add_u32 s40, s22, 0x1c101000
	s_addc_u32 s41, s23, 0
	s_add_u32 s42, s22, 0x1c101100
	s_addc_u32 s43, s23, 0
	s_add_u32 s44, s22, 0x1c101200
	s_addc_u32 s45, s23, 0
	s_add_u32 s46, s22, 0x1c101300
	s_addc_u32 s47, s23, 0
	s_mov_b32 s1, 1
	v_mov_b32_e32 v16, 0
	s_branch .LBB0_1656

; __global__ void __launch_bounds__(256, 2) fwd_megakernel(Params p) {
;     ...
;   __shared__ __attribute__((aligned(16))) unsigned char smem[SMEM_BYTES];
;   unsigned char* ws = p.ws;
;   __shared__ __attribute__((aligned(16))) unsigned xb_words[4];
	.amdhsa_kernel _Z14fwd_megakernel6Params
		.amdhsa_group_segment_fixed_size 73744
		.amdhsa_private_segment_fixed_size 0
		.amdhsa_kernarg_size 776
		.amdhsa_user_sgpr_count 2
		.amdhsa_user_sgpr_dispatch_ptr 0
		.amdhsa_user_sgpr_queue_ptr 0
		.amdhsa_user_sgpr_kernarg_segment_ptr 1
		.amdhsa_user_sgpr_dispatch_id 0
		.amdhsa_user_sgpr_kernarg_preload_length 0
		.amdhsa_user_sgpr_kernarg_preload_offset 0
		.amdhsa_user_sgpr_private_segment_size 0
		.amdhsa_uses_dynamic_stack 0
		.amdhsa_enable_private_segment 0
		.amdhsa_system_sgpr_workgroup_id_x 1
		.amdhsa_system_sgpr_workgroup_id_y 0
		.amdhsa_system_sgpr_workgroup_id_z 0
		.amdhsa_system_sgpr_workgroup_info 0
		.amdhsa_system_vgpr_workitem_id 2
		.amdhsa_next_free_vgpr 256
		.amdhsa_next_free_sgpr 102
		.amdhsa_accum_offset 256
		.amdhsa_reserve_vcc 1
		.amdhsa_float_round_mode_32 0
		.amdhsa_float_round_mode_16_64 0
		.amdhsa_float_denorm_mode_32 3
		.amdhsa_float_denorm_mode_16_64 3
		.amdhsa_dx10_clamp 1
		.amdhsa_ieee_mode 1
		.amdhsa_fp16_overflow 0
		.amdhsa_tg_split 0
		.amdhsa_exception_fp_ieee_invalid_op 0
		.amdhsa_exception_fp_denorm_src 0
		.amdhsa_exception_fp_ieee_div_zero 0
		.amdhsa_exception_fp_ieee_overflow 0
		.amdhsa_exception_fp_ieee_underflow 0
		.amdhsa_exception_fp_ieee_inexact 0
		.amdhsa_exception_int_div_zero 0
	.end_amdhsa_kernel

; __global__ void __launch_bounds__(256, 2) fwd_megakernel(Params p) {
;     ...
;   __shared__ __attribute__((aligned(16))) unsigned char smem[SMEM_BYTES];
;   unsigned char* ws = p.ws;
;   __shared__ __attribute__((aligned(16))) unsigned xb_words[4];
amdhsa.kernels:
  - .agpr_count:     0
    .args:
      - .offset:         0
        .size:           520
        .value_kind:     by_value
      - .offset:         520
        .size:           4
        .value_kind:     hidden_block_count_x
      - .offset:         524
        .size:           4
        .value_kind:     hidden_block_count_y
      - .offset:         528
        .size:           4
        .value_kind:     hidden_block_count_z
      - .offset:         532
        .size:           2
        .value_kind:     hidden_group_size_x
      - .offset:         534
        .size:           2
        .value_kind:     hidden_group_size_y
      - .offset:         536
        .size:           2
        .value_kind:     hidden_group_size_z
      - .offset:         538
        .size:           2
        .value_kind:     hidden_remainder_x
      - .offset:         540
        .size:           2
        .value_kind:     hidden_remainder_y
      - .offset:         542
        .size:           2
        .value_kind:     hidden_remainder_z
      - .offset:         560
        .size:           8
        .value_kind:     hidden_global_offset_x
      - .offset:         568
        .size:           8
        .value_kind:     hidden_global_offset_y
      - .offset:         576
        .size:           8
        .value_kind:     hidden_global_offset_z
      - .offset:         584
        .size:           2
        .value_kind:     hidden_grid_dims
      - .offset:         608
        .size:           8
        .value_kind:     hidden_multigrid_sync_arg
    .group_segment_fixed_size: 73744
    .kernarg_segment_align: 8
    .kernarg_segment_size: 776
    .language:       OpenCL C
    .language_version:
      - 2
      - 0
    .max_flat_workgroup_size: 256
    .name:           _Z14fwd_megakernel6Params
    .private_segment_fixed_size: 0
    .sgpr_count:     108
    .sgpr_spill_count: 16
    .symbol:         _Z14fwd_megakernel6Params.kd
    .uniform_work_group_size: 1
    .uses_dynamic_stack: false
    .vgpr_count:     256
    .vgpr_spill_count: 0
    .wavefront_size: 64
